# static s_setprio 1 for waves 4-7 across GEMM phases (win/gemm_f32/ffn_up), per-iteration priority toggles removed
# speedup vs baseline: 1.0167x; 1.0023x over previous
; template <int MI, int NJ> ...
;   const int lane = tid & 63, wave = tid >> 6;
;   const int wm = wave >> 2, wn = wave & 3;
;   constexpr int AROWS = 32 * MI;
;   constexpr int BROWS = 64 * NJ;
;   u16* sA = smem;
;   u16* sB = smem + 2 * AROWS * 64;
;   const int lrow = tid >> 3, lkc = tid & 7;
;   const u16* Ag = A + (size_t)(row0 + lrow) * lda + kbeg + lkc * 8;
;   const u16* Bg = Bt + (size_t)(col0 + lrow) * ldb + kbeg + lkc * 8;
;   const size_t a64 = (size_t)64 * lda, b64 = (size_t)64 * ldb;
;   const int nk = (kend - kbeg) >> 6;
;   const long long nAoff = (long long)(nrow0 - row0) * lda + (nkbeg - kbeg);
;   const long long nBoff = (long long)(ncol0 - col0) * ldb + (nkbeg - kbeg);
;   u16* wa = sA + lrow * 64 + ((lkc ^ (lrow & 7)) * 8);
;   u16* wb = sB + lrow * 64 + ((lkc ^ (lrow & 7)) * 8);
;     ...
;   if (!pre) G8LOADP(Ag, Bg);
;   G8STORE(0);
;   {
;     const u16* ga_ = (1 < nk) ? Ag + 64 : Ag + nAoff;
;     const u16* gb_ = (1 < nk) ? Bg + 64 : Bg + nBoff;
;     G8LOADP(ga_, gb_);
;   }
;   __syncthreads();
;   const int sw0 = ((lane >> 4) ^ (lane & 7)) * 8;
;   const int dsw = (sw0 ^ 32) - sw0;
;   const u16* ra_ = sA + (wm * (16 * MI) + (lane & 15)) * 64 + sw0;
;   const u16* rb_ = sB + (wn * (16 * NJ) + (lane & 15)) * 64 + sw0;
.LBB0_439:
	s_waitcnt vmcnt(15)
	v_mov_b32_e32 v2, v175
	ds_read_b32 v0, v230
	s_waitcnt lgkmcnt(0)
	v_readfirstlane_b32 s0, v0
	s_ashr_i32 s38, s0, 3
	s_cmp_ge_i32 s38, s22
	s_cbranch_scc1 .LBB0_472
	s_lshl_b32 s0, s0, 3
	s_and_b32 s23, s0, 56
	v_lshlrev_b32_e32 v0, 4, v2
	v_readlane_b32 s0, v252, 38
	v_and_b32_e32 v0, 0x70, v0
	v_readlane_b32 s1, v252, 39
	v_ashrrev_i32_e32 v184, 3, v2
	v_and_b32_e32 v3, 7, v2
	v_lshl_add_u64 v[176:177], s[0:1], 0, v[0:1]
	v_readlane_b32 s0, v253, 7
	v_readlane_b32 s1, v253, 8
	s_mov_b64 s[12:13], 0
	s_nop 0
	v_lshl_add_u64 v[178:179], s[0:1], 0, v[0:1]
	v_and_b32_e32 v234, 7, v184
	v_lshl_add_u32 v234, v234, 11, v0
	v_add_u32_e32 v235, 0x20000, v234
	v_add_u32_e32 v236, 0x40000, v234
	v_add_u32_e32 v237, 0x60000, v234
	v_cmp_lt_u32_e32 vcc, 0xff, v175
	s_cbranch_vccz .Lprio_skip_win
	s_setprio 1
.Lprio_skip_win:
	v_xor_b32_e32 v0, v184, v2
	v_lshlrev_b32_e32 v0, 4, v0
	v_and_b32_e32 v0, 0x70, v0
	v_lshl_or_b32 v185, v184, 7, v0
	v_lshrrev_b32_e32 v0, 4, v2
	v_bitop3_b32 v0, v0, v3, 3 bitop3:0x6c
	v_lshlrev_b32_e32 v3, 3, v0
	v_xor_b32_e32 v4, 32, v3
	v_sub_u32_e32 v3, v4, v3
	v_ashrrev_i32_e32 v4, 1, v2
	v_and_b32_e32 v4, 0xffffff80, v4
	v_and_or_b32 v5, v2, 15, v4
	v_lshlrev_b32_e32 v0, 4, v0
	v_lshl_or_b32 v187, v5, 7, v0
	v_lshlrev_b32_e32 v5, 7, v2
	v_and_b32_e32 v5, 0x6780, v5
	s_mov_b32 s0, 0x10000
	v_or3_b32 v188, v5, v0, s0
	v_lshrrev_b32_e32 v0, 2, v2
	v_and_or_b32 v0, v0, 12, v4
	v_and_b32_e32 v2, 0xcf, v2
	v_mul_lo_u32 v0, v0, s2
	v_lshl_add_u32 v189, v2, 1, v0
	v_mov_b32_e32 v0, v1
	v_add_u32_e32 v186, 0x10000, v185
	v_lshlrev_b32_e32 v190, 1, v3
	s_waitcnt vmcnt(10)
	v_mov_b64_e32 v[22:23], v[0:1]
	v_mov_b64_e32 v[24:25], v[0:1]
	s_waitcnt vmcnt(9)
	v_mov_b64_e32 v[26:27], v[0:1]
	s_waitcnt vmcnt(12)
	v_mov_b64_e32 v[28:29], v[0:1]
	s_waitcnt vmcnt(8)
	v_mov_b64_e32 v[30:31], v[0:1]
	s_waitcnt vmcnt(4)
	v_mov_b64_e32 v[32:33], v[0:1]

; template <int MI, int NJ> ...
;     ...
;   for (int kt = 0; kt < nk; ++kt) {
;     const int buf = kt & 1;
;     {
;       G8STORE(buf ^ 1);
;       const u16* ga_ = (kt + 2 < nk) ? Ag + (kt + 2) * 64 : Ag + nAoff;
;       const u16* gb_ = (kt + 2 < nk) ? Bg + (kt + 2) * 64 : Bg + nBoff;
;       G8LOADP(ga_, gb_);
;     }
;     __builtin_amdgcn_sched_barrier(0);
;     __builtin_amdgcn_s_setprio(1);
;     const u16* a = ra_ + buf * AROWS * 64;
;     const u16* b = rb_ + buf * BROWS * 64;
; #pragma unroll
;     for (int ks = 0; ks < 2; ++ks) {
;       const u16* a_ = ks ? a + dsw : a;
;       const u16* b_ = ks ? b + dsw : b;
;       bf16x8 bfr[NJ];
; #pragma unroll
;       for (int j = 0; j < NJ; ++j) bfr[j] = *(const bf16x8*)(b_ + j * 16 * 64);
; #pragma unroll
;       for (int ih = 0; ih < MI / 4; ++ih) {
;         bf16x8 af[4];
; #pragma unroll
;         for (int i = 0; i < 4; ++i) af[i] = *(const bf16x8*)(a_ + (ih * 4 + i) * 16 * 64);
; #pragma unroll
;         for (int i = 0; i < 4; ++i)
; #pragma unroll
;           for (int j = 0; j < NJ; ++j) acc[ih * 4 + i][j] = mfma16(af[i], bfr[j], acc[ih * 4 + i][j]);
;       }
;     }
;     __builtin_amdgcn_s_setprio(0);
;     __builtin_amdgcn_sched_barrier(0);
;     __syncthreads();
;   }
.LBB0_470:
	s_waitcnt lgkmcnt(6)
	v_mfma_f32_16x16x32_bf16 v[158:161], v[166:169], v[162:165], v[158:161]
	s_waitcnt lgkmcnt(5)
	v_mfma_f32_16x16x32_bf16 v[154:157], v[170:173], v[162:165], v[154:157]
	s_waitcnt lgkmcnt(4)
	v_mfma_f32_16x16x32_bf16 v[150:153], v[192:195], v[162:165], v[150:153]
	s_waitcnt lgkmcnt(3)
	v_mfma_f32_16x16x32_bf16 v[146:149], v[196:199], v[162:165], v[146:149]
	ds_read_b128 v[162:165], v0 offset:8192
	s_waitcnt lgkmcnt(3)
	v_mfma_f32_16x16x32_bf16 v[142:145], v[166:169], v[204:207], v[142:145]
	v_mfma_f32_16x16x32_bf16 v[138:141], v[170:173], v[204:207], v[138:141]
	v_mfma_f32_16x16x32_bf16 v[134:137], v[192:195], v[204:207], v[134:137]
	v_mfma_f32_16x16x32_bf16 v[130:133], v[196:199], v[204:207], v[130:133]
	ds_read_b128 v[204:207], v0 offset:10240
	s_waitcnt lgkmcnt(3)
	v_mfma_f32_16x16x32_bf16 v[126:129], v[166:169], v[208:211], v[126:129]
	v_mfma_f32_16x16x32_bf16 v[122:125], v[170:173], v[208:211], v[122:125]
	v_mfma_f32_16x16x32_bf16 v[118:121], v[192:195], v[208:211], v[118:121]
	v_mfma_f32_16x16x32_bf16 v[114:117], v[196:199], v[208:211], v[114:117]
	ds_read_b128 v[208:211], v0 offset:12288
	ds_read_b128 v[212:215], v191
	ds_read_b128 v[216:219], v191 offset:2048
	s_waitcnt lgkmcnt(5)
	v_mfma_f32_16x16x32_bf16 v[110:113], v[166:169], v[238:241], v[110:113]
	v_mfma_f32_16x16x32_bf16 v[106:109], v[170:173], v[238:241], v[106:109]
	v_mfma_f32_16x16x32_bf16 v[102:105], v[192:195], v[238:241], v[102:105]
	v_mfma_f32_16x16x32_bf16 v[98:101], v[196:199], v[238:241], v[98:101]
	ds_read_b128 v[238:241], v0 offset:14336
	ds_read_b128 v[220:223], v191 offset:4096
	ds_read_b128 v[224:227], v191 offset:6144
	s_waitcnt lgkmcnt(7)
	v_mfma_f32_16x16x32_bf16 v[94:97], v[166:169], v[162:165], v[94:97]
	v_mfma_f32_16x16x32_bf16 v[90:93], v[170:173], v[162:165], v[90:93]
	v_mfma_f32_16x16x32_bf16 v[86:89], v[192:195], v[162:165], v[86:89]
	v_mfma_f32_16x16x32_bf16 v[82:85], v[196:199], v[162:165], v[82:85]
	v_add_u32_e32 v0, v0, v190
	ds_read_b128 v[162:165], v0
	s_waitcnt vmcnt(7)
	ds_write_b128 v228, v[10:13]
	global_load_dwordx4 v[10:13], v234, s[52:53]
	s_waitcnt lgkmcnt(8)
	v_mfma_f32_16x16x32_bf16 v[78:81], v[166:169], v[204:207], v[78:81]
	v_mfma_f32_16x16x32_bf16 v[74:77], v[170:173], v[204:207], v[74:77]
	v_mfma_f32_16x16x32_bf16 v[70:73], v[192:195], v[204:207], v[70:73]
	v_mfma_f32_16x16x32_bf16 v[66:69], v[196:199], v[204:207], v[66:69]
	ds_read_b128 v[204:207], v0 offset:2048
	s_waitcnt vmcnt(7)
	ds_write_b128 v228, v[2:5] offset:8192
	global_load_dwordx4 v[2:5], v235, s[52:53]
	s_waitcnt lgkmcnt(9)
	v_mfma_f32_16x16x32_bf16 v[62:65], v[166:169], v[208:211], v[62:65]
	v_mfma_f32_16x16x32_bf16 v[58:61], v[170:173], v[208:211], v[58:61]
	v_mfma_f32_16x16x32_bf16 v[54:57], v[192:195], v[208:211], v[54:57]
	v_mfma_f32_16x16x32_bf16 v[50:53], v[196:199], v[208:211], v[50:53]
	ds_read_b128 v[208:211], v0 offset:4096
	s_waitcnt vmcnt(7)
	ds_write_b128 v228, v[6:9] offset:16384
	global_load_dwordx4 v[6:9], v236, s[52:53]
	s_waitcnt lgkmcnt(8)
	v_mfma_f32_16x16x32_bf16 v[46:49], v[166:169], v[238:241], v[46:49]
	v_mfma_f32_16x16x32_bf16 v[42:45], v[170:173], v[238:241], v[42:45]
	v_mfma_f32_16x16x32_bf16 v[38:41], v[192:195], v[238:241], v[38:41]
	v_mfma_f32_16x16x32_bf16 v[34:37], v[196:199], v[238:241], v[34:37]
	ds_read_b128 v[238:241], v0 offset:6144
	s_waitcnt vmcnt(7)
	ds_write_b128 v228, v[18:21] offset:24576
	global_load_dwordx4 v[18:21], v237, s[52:53]
	s_waitcnt lgkmcnt(7)
	v_mfma_f32_16x16x32_bf16 v[158:161], v[212:215], v[162:165], v[158:161]
	v_mfma_f32_16x16x32_bf16 v[154:157], v[216:219], v[162:165], v[154:157]
	v_mfma_f32_16x16x32_bf16 v[150:153], v[220:223], v[162:165], v[150:153]
	v_mfma_f32_16x16x32_bf16 v[146:149], v[224:227], v[162:165], v[146:149]
	ds_read_b128 v[162:165], v0 offset:8192
	s_waitcnt vmcnt(7)
	ds_write_b128 v229, v[14:17]
	global_load_dwordx4 v[14:17], v234, s[66:67]
	s_waitcnt lgkmcnt(7)
	v_mfma_f32_16x16x32_bf16 v[142:145], v[212:215], v[204:207], v[142:145]
	v_mfma_f32_16x16x32_bf16 v[138:141], v[216:219], v[204:207], v[138:141]
	v_mfma_f32_16x16x32_bf16 v[134:137], v[220:223], v[204:207], v[134:137]
	v_mfma_f32_16x16x32_bf16 v[130:133], v[224:227], v[204:207], v[130:133]
	ds_read_b128 v[204:207], v0 offset:10240
	s_waitcnt vmcnt(7)
	ds_write_b128 v229, v[22:25] offset:8192
	global_load_dwordx4 v[22:25], v235, s[66:67]
	s_waitcnt lgkmcnt(7)
	v_mfma_f32_16x16x32_bf16 v[126:129], v[212:215], v[208:211], v[126:129]
	v_mfma_f32_16x16x32_bf16 v[122:125], v[216:219], v[208:211], v[122:125]
	v_mfma_f32_16x16x32_bf16 v[118:121], v[220:223], v[208:211], v[118:121]
	v_mfma_f32_16x16x32_bf16 v[114:117], v[224:227], v[208:211], v[114:117]
	ds_read_b128 v[208:211], v0 offset:12288
	s_waitcnt vmcnt(7)
	ds_write_b128 v229, v[26:29] offset:16384
	global_load_dwordx4 v[26:29], v236, s[66:67]
	s_waitcnt lgkmcnt(7)
	v_mfma_f32_16x16x32_bf16 v[110:113], v[212:215], v[238:241], v[110:113]
	v_mfma_f32_16x16x32_bf16 v[106:109], v[216:219], v[238:241], v[106:109]
	v_mfma_f32_16x16x32_bf16 v[102:105], v[220:223], v[238:241], v[102:105]
	v_mfma_f32_16x16x32_bf16 v[98:101], v[224:227], v[238:241], v[98:101]
	ds_read_b128 v[238:241], v0 offset:14336
	s_waitcnt vmcnt(7)
	ds_write_b128 v229, v[30:33] offset:24576
	global_load_dwordx4 v[30:33], v237, s[66:67]
	s_waitcnt lgkmcnt(7)
	v_mfma_f32_16x16x32_bf16 v[94:97], v[212:215], v[162:165], v[94:97]
	v_mfma_f32_16x16x32_bf16 v[90:93], v[216:219], v[162:165], v[90:93]
	v_mfma_f32_16x16x32_bf16 v[86:89], v[220:223], v[162:165], v[86:89]
	v_mfma_f32_16x16x32_bf16 v[82:85], v[224:227], v[162:165], v[82:85]
	s_waitcnt lgkmcnt(0)
	s_barrier
; template <int MI, int NJ> ...
;     ...
;     const u16* a = ra_ + buf * AROWS * 64;
;     const u16* b = rb_ + buf * BROWS * 64;
; #pragma unroll
;     for (int ks = 0; ks < 2; ++ks) {
;       const u16* a_ = ks ? a + dsw : a;
;       const u16* b_ = ks ? b + dsw : b;
;       bf16x8 bfr[NJ];
; #pragma unroll
;       for (int j = 0; j < NJ; ++j) bfr[j] = *(const bf16x8*)(b_ + j * 16 * 64);
; #pragma unroll
;       for (int ih = 0; ih < MI / 4; ++ih) {
;         bf16x8 af[4];
; #pragma unroll
;         for (int i = 0; i < 4; ++i) af[i] = *(const bf16x8*)(a_ + (ih * 4 + i) * 16 * 64);
; #pragma unroll
;         for (int i = 0; i < 4; ++i)
; #pragma unroll
;           for (int j = 0; j < NJ; ++j) acc[ih * 4 + i][j] = mfma16(af[i], bfr[j], acc[ih * 4 + i][j]);
;       }
;     }
; __device__ __forceinline__ void phase_win(const Params& p, int part, u16* smem, volatile LAS unsigned* vb_) {
;     ...
; #pragma unroll
;     for (int i = 0; i < 8; ++i)
; #pragma unroll
;       for (int j = 0; j < 4; ++j)
; #pragma unroll
;         for (int r = 0; r < 4; ++r)
;           smem[(wm * 128 + i * 16 + (lane >> 4) * 4 + r) * 264 + wn * 64 + j * 16 + (lane & 15)] = f2bf(acc[i][j][r]);
;     __syncthreads();
	s_add_i32 s37, s37, 1
	s_add_u32 s20, s20, 64
	s_addc_u32 s21, s21, 0
	s_addk_i32 s11, 0x4000
	s_and_b32 s38, s11, 0x4000
	s_xor_b32 s39, s38, 0x4000
	s_lshl_b32 s39, s39, 1
	v_add_u32_e32 v228, s39, v185
	v_add_u32_e32 v229, s39, v186
	s_cmp_lt_u32 s37, 14
	s_cselect_b32 s49, s21, s13
	s_cselect_b32 s48, s20, s12
	s_cselect_b32 s51, s21, s47
	s_cselect_b32 s50, s20, s46
	s_lshl_b64 s[48:49], s[48:49], 1
	s_lshl_b64 s[50:51], s[50:51], 1
	s_add_u32 s52, s62, s48
	s_addc_u32 s53, s63, s49
	s_add_u32 s66, s64, s50
	s_addc_u32 s67, s65, s51
	s_lshl_b32 s38, s38, 1
	v_add_u32_e32 v0, s38, v187
	v_add_u32_e32 v191, s38, v188
	ds_read_b128 v[166:169], v191
	ds_read_b128 v[162:165], v0
	ds_read_b128 v[170:173], v191 offset:2048
	ds_read_b128 v[192:195], v191 offset:4096
	ds_read_b128 v[196:199], v191 offset:6144
	v_mfma_f32_16x16x32_bf16 v[78:81], v[212:215], v[204:207], v[78:81]
	v_mfma_f32_16x16x32_bf16 v[74:77], v[216:219], v[204:207], v[74:77]
	v_mfma_f32_16x16x32_bf16 v[70:73], v[220:223], v[204:207], v[70:73]
	v_mfma_f32_16x16x32_bf16 v[66:69], v[224:227], v[204:207], v[66:69]
	ds_read_b128 v[204:207], v0 offset:2048
	v_mfma_f32_16x16x32_bf16 v[62:65], v[212:215], v[208:211], v[62:65]
	v_mfma_f32_16x16x32_bf16 v[58:61], v[216:219], v[208:211], v[58:61]
	v_mfma_f32_16x16x32_bf16 v[54:57], v[220:223], v[208:211], v[54:57]
	v_mfma_f32_16x16x32_bf16 v[50:53], v[224:227], v[208:211], v[50:53]
	ds_read_b128 v[208:211], v0 offset:4096
	v_mfma_f32_16x16x32_bf16 v[46:49], v[212:215], v[238:241], v[46:49]
	v_mfma_f32_16x16x32_bf16 v[42:45], v[216:219], v[238:241], v[42:45]
	v_mfma_f32_16x16x32_bf16 v[38:41], v[220:223], v[238:241], v[38:41]
	v_mfma_f32_16x16x32_bf16 v[34:37], v[224:227], v[238:241], v[34:37]
	ds_read_b128 v[238:241], v0 offset:6144
	v_add_u32_e32 v191, v191, v190
	s_cmpk_lg_i32 s20, 0x480
	s_cbranch_scc1 .LBB0_470
	v_and_b32_e32 v228, 15, v175
	v_bfe_u32 v229, v175, 8, 1
	v_lshl_or_b32 v228, v229, 7, v228
	v_mul_u32_u24_e32 v228, 0x210, v228
	v_bfe_u32 v229, v175, 6, 2
	v_lshl_add_u32 v228, v229, 7, v228
	v_bfe_u32 v229, v175, 4, 2
	v_lshl_add_u32 v228, v229, 3, v228
	v_cvt_pk_bf16_f32 v158, v158, v159
	v_cvt_pk_bf16_f32 v159, v160, v161
	v_cvt_pk_bf16_f32 v154, v154, v155
	v_cvt_pk_bf16_f32 v155, v156, v157
	v_cvt_pk_bf16_f32 v150, v150, v151
	v_cvt_pk_bf16_f32 v151, v152, v153
	v_cvt_pk_bf16_f32 v146, v146, v147
	v_cvt_pk_bf16_f32 v147, v148, v149
	ds_write_b64 v228, v[158:159]
	ds_write_b64 v228, v[154:155] offset:32
	ds_write_b64 v228, v[150:151] offset:64
	ds_write_b64 v228, v[146:147] offset:96
	v_cvt_pk_bf16_f32 v142, v142, v143
	v_cvt_pk_bf16_f32 v143, v144, v145
	v_cvt_pk_bf16_f32 v138, v138, v139
	v_cvt_pk_bf16_f32 v139, v140, v141
	v_cvt_pk_bf16_f32 v134, v134, v135
	v_cvt_pk_bf16_f32 v135, v136, v137
	v_cvt_pk_bf16_f32 v130, v130, v131
	v_cvt_pk_bf16_f32 v131, v132, v133
	ds_write_b64 v228, v[142:143] offset:8448
	ds_write_b64 v228, v[138:139] offset:8480
	ds_write_b64 v228, v[134:135] offset:8512
	ds_write_b64 v228, v[130:131] offset:8544
	v_cvt_pk_bf16_f32 v126, v126, v127
	v_cvt_pk_bf16_f32 v127, v128, v129
	v_cvt_pk_bf16_f32 v122, v122, v123
	v_cvt_pk_bf16_f32 v123, v124, v125
	v_cvt_pk_bf16_f32 v118, v118, v119
	v_cvt_pk_bf16_f32 v119, v120, v121
	v_cvt_pk_bf16_f32 v114, v114, v115
	v_cvt_pk_bf16_f32 v115, v116, v117
	ds_write_b64 v228, v[126:127] offset:16896
	ds_write_b64 v228, v[122:123] offset:16928
	ds_write_b64 v228, v[118:119] offset:16960
	ds_write_b64 v228, v[114:115] offset:16992
	v_cvt_pk_bf16_f32 v110, v110, v111
	v_cvt_pk_bf16_f32 v111, v112, v113
	v_cvt_pk_bf16_f32 v106, v106, v107
	v_cvt_pk_bf16_f32 v107, v108, v109
	v_cvt_pk_bf16_f32 v102, v102, v103
	v_cvt_pk_bf16_f32 v103, v104, v105
	v_cvt_pk_bf16_f32 v98, v98, v99
	v_cvt_pk_bf16_f32 v99, v100, v101
	ds_write_b64 v228, v[110:111] offset:25344
	ds_write_b64 v228, v[106:107] offset:25376
	ds_write_b64 v228, v[102:103] offset:25408
	ds_write_b64 v228, v[98:99] offset:25440
	v_cvt_pk_bf16_f32 v94, v94, v95
	v_cvt_pk_bf16_f32 v95, v96, v97
	v_cvt_pk_bf16_f32 v90, v90, v91
	v_cvt_pk_bf16_f32 v91, v92, v93
	v_cvt_pk_bf16_f32 v86, v86, v87
	v_cvt_pk_bf16_f32 v87, v88, v89
	v_cvt_pk_bf16_f32 v82, v82, v83
	v_cvt_pk_bf16_f32 v83, v84, v85
	ds_write_b64 v228, v[94:95] offset:33792
	ds_write_b64 v228, v[90:91] offset:33824
	ds_write_b64 v228, v[86:87] offset:33856
	ds_write_b64 v228, v[82:83] offset:33888
	v_cvt_pk_bf16_f32 v78, v78, v79
	v_cvt_pk_bf16_f32 v79, v80, v81
	v_cvt_pk_bf16_f32 v74, v74, v75
	v_cvt_pk_bf16_f32 v75, v76, v77
	v_cvt_pk_bf16_f32 v70, v70, v71
	v_cvt_pk_bf16_f32 v71, v72, v73
	v_cvt_pk_bf16_f32 v66, v66, v67
	v_cvt_pk_bf16_f32 v67, v68, v69
	ds_write_b64 v228, v[78:79] offset:42240
	ds_write_b64 v228, v[74:75] offset:42272
	ds_write_b64 v228, v[70:71] offset:42304
	ds_write_b64 v228, v[66:67] offset:42336
	v_cvt_pk_bf16_f32 v62, v62, v63
	v_cvt_pk_bf16_f32 v63, v64, v65
	v_cvt_pk_bf16_f32 v58, v58, v59
	v_cvt_pk_bf16_f32 v59, v60, v61
	v_cvt_pk_bf16_f32 v54, v54, v55
	v_cvt_pk_bf16_f32 v55, v56, v57
	v_cvt_pk_bf16_f32 v50, v50, v51
	v_cvt_pk_bf16_f32 v51, v52, v53
	ds_write_b64 v228, v[62:63] offset:50688
	ds_write_b64 v228, v[58:59] offset:50720
	ds_write_b64 v228, v[54:55] offset:50752
	ds_write_b64 v228, v[50:51] offset:50784
	v_cvt_pk_bf16_f32 v46, v46, v47
	v_cvt_pk_bf16_f32 v47, v48, v49
	v_cvt_pk_bf16_f32 v42, v42, v43
	v_cvt_pk_bf16_f32 v43, v44, v45
	v_cvt_pk_bf16_f32 v38, v38, v39
	v_cvt_pk_bf16_f32 v39, v40, v41
	v_cvt_pk_bf16_f32 v34, v34, v35
	v_cvt_pk_bf16_f32 v35, v36, v37
	ds_write_b64 v228, v[46:47] offset:59136
	ds_write_b64 v228, v[42:43] offset:59168
	ds_write_b64 v228, v[38:39] offset:59200
	ds_write_b64 v228, v[34:35] offset:59232
	v_mov_b32_e32 v43, v175
	s_waitcnt lgkmcnt(0)
	s_barrier
; #define RTID opaque_tid()
; __device__ __forceinline__ void phase_win(const Params& p, int part, u16* smem, volatile LAS unsigned* vb_) {
;     ...
;     const int tid2 = RTID;
; #pragma unroll
;     for (int k = 0; k < 16; ++k) {
;       const int c = tid2 + 512 * k;
;       const int row = c >> 5, ch = c & 31;
;       const uint4 v = *(const uint4*)(smem + row * 264 + ch * 8);
;       u16* d_ = (ch < 16) ? dstA : dstB;
;       const int l_ = (ch < 16) ? ldA : ldB;
;       *(uint4*)(d_ + (size_t)(mt * 256 + row) * l_ + (ch & 15) * 8) = v;
;     }
;     __syncthreads();
	s_mov_b32 s38, s36
	v_and_b32_e32 v0, 31, v43
	v_lshlrev_b32_e32 v42, 4, v0
	v_cmp_gt_u32_e32 vcc, 16, v0
	v_mov_b32_e32 v0, 0x100
	s_nop 0
	v_cndmask_b32_e64 v0, v0, 0, vcc
	v_lshl_add_u64 v[34:35], s[44:45], 0, v[0:1]
	v_lshlrev_b32_e32 v0, 4, v43
	v_and_b32_e32 v0, 0xf0, v0
	v_lshl_add_u64 v[44:45], v[34:35], 0, v[0:1]
	v_ashrrev_i32_e32 v0, 5, v43
	v_mad_u64_u32 v[34:35], s[12:13], v0, s2, v[42:43]
	v_add_u32_e32 v0, s10, v0
	ds_read_b128 v[34:37], v34
	v_ashrrev_i32_e32 v38, 31, v0
	v_mul_lo_u32 v40, s0, v38
	v_mul_lo_u32 v41, s1, v0
	v_mad_u64_u32 v[38:39], s[12:13], s0, v0, 0
	v_add_u32_e32 v0, 0x200, v43
	v_add3_u32 v39, v39, v40, v41
	v_ashrrev_i32_e32 v0, 5, v0
	v_lshl_add_u64 v[46:47], v[38:39], 1, v[44:45]
	v_mad_u64_u32 v[38:39], s[12:13], v0, s2, v[42:43]
	ds_read_b128 v[38:41], v38
	v_add_u32_e32 v0, s10, v0
	s_waitcnt lgkmcnt(1)
	global_store_dwordx4 v[46:47], v[34:37], off
	s_and_b64 vcc, exec, s[42:43]
	s_nop 0
	v_ashrrev_i32_e32 v34, 31, v0
	v_mul_lo_u32 v36, s0, v34
	v_mul_lo_u32 v37, s1, v0
	v_mad_u64_u32 v[34:35], s[12:13], s0, v0, 0
	v_add3_u32 v35, v35, v36, v37
	v_add_u32_e32 v0, 0x400, v43
	v_lshl_add_u64 v[34:35], v[34:35], 1, v[44:45]
	v_ashrrev_i32_e32 v0, 5, v0
	s_waitcnt lgkmcnt(0)
	global_store_dwordx4 v[34:35], v[38:41], off
	v_mad_u64_u32 v[34:35], s[12:13], v0, s2, v[42:43]
	v_add_u32_e32 v0, s10, v0
	ds_read_b128 v[34:37], v34
	v_ashrrev_i32_e32 v38, 31, v0
	v_mul_lo_u32 v40, s0, v38
	v_mul_lo_u32 v41, s1, v0
	v_mad_u64_u32 v[38:39], s[12:13], s0, v0, 0
	v_add_u32_e32 v0, 0x600, v43
	v_add3_u32 v39, v39, v40, v41
	v_ashrrev_i32_e32 v0, 5, v0
	v_lshl_add_u64 v[46:47], v[38:39], 1, v[44:45]
	v_mad_u64_u32 v[38:39], s[12:13], v0, s2, v[42:43]
	ds_read_b128 v[38:41], v38
	v_add_u32_e32 v0, s10, v0
	s_waitcnt lgkmcnt(1)
	global_store_dwordx4 v[46:47], v[34:37], off
	s_nop 1
	v_ashrrev_i32_e32 v34, 31, v0
	v_mul_lo_u32 v36, s0, v34
	v_mul_lo_u32 v37, s1, v0
	v_mad_u64_u32 v[34:35], s[12:13], s0, v0, 0
	v_add3_u32 v35, v35, v36, v37
	v_add_u32_e32 v0, 0x800, v43
	v_lshl_add_u64 v[34:35], v[34:35], 1, v[44:45]
	v_ashrrev_i32_e32 v0, 5, v0
	s_waitcnt lgkmcnt(0)
	global_store_dwordx4 v[34:35], v[38:41], off
	v_mad_u64_u32 v[34:35], s[12:13], v0, s2, v[42:43]
	v_add_u32_e32 v0, s10, v0
	ds_read_b128 v[34:37], v34
	v_ashrrev_i32_e32 v38, 31, v0
	v_mul_lo_u32 v40, s0, v38
	v_mul_lo_u32 v41, s1, v0
	v_mad_u64_u32 v[38:39], s[12:13], s0, v0, 0
	v_add_u32_e32 v0, 0xa00, v43
	v_add3_u32 v39, v39, v40, v41
	v_ashrrev_i32_e32 v0, 5, v0
	v_lshl_add_u64 v[46:47], v[38:39], 1, v[44:45]
	v_mad_u64_u32 v[38:39], s[12:13], v0, s2, v[42:43]
	ds_read_b128 v[38:41], v38
	v_add_u32_e32 v0, s10, v0
	s_waitcnt lgkmcnt(1)
	global_store_dwordx4 v[46:47], v[34:37], off
	s_nop 1
	v_ashrrev_i32_e32 v34, 31, v0
	v_mul_lo_u32 v36, s0, v34
	v_mul_lo_u32 v37, s1, v0
	v_mad_u64_u32 v[34:35], s[12:13], s0, v0, 0
	v_add3_u32 v35, v35, v36, v37
	v_add_u32_e32 v0, 0xc00, v43
	v_lshl_add_u64 v[34:35], v[34:35], 1, v[44:45]
	v_ashrrev_i32_e32 v0, 5, v0
	s_waitcnt lgkmcnt(0)
	global_store_dwordx4 v[34:35], v[38:41], off
	v_mad_u64_u32 v[34:35], s[12:13], v0, s2, v[42:43]
	v_add_u32_e32 v0, s10, v0
	ds_read_b128 v[34:37], v34
	v_ashrrev_i32_e32 v38, 31, v0
	v_mul_lo_u32 v40, s0, v38
	v_mul_lo_u32 v41, s1, v0
	v_mad_u64_u32 v[38:39], s[12:13], s0, v0, 0
	v_add_u32_e32 v0, 0xe00, v43
	v_add3_u32 v39, v39, v40, v41
	v_ashrrev_i32_e32 v0, 5, v0
	v_lshl_add_u64 v[46:47], v[38:39], 1, v[44:45]
	v_mad_u64_u32 v[38:39], s[12:13], v0, s2, v[42:43]
	ds_read_b128 v[38:41], v38
	v_add_u32_e32 v0, s10, v0
	s_waitcnt lgkmcnt(1)
	global_store_dwordx4 v[46:47], v[34:37], off
	s_nop 1
	v_ashrrev_i32_e32 v34, 31, v0
	v_mul_lo_u32 v36, s0, v34
	v_mul_lo_u32 v37, s1, v0
	v_mad_u64_u32 v[34:35], s[12:13], s0, v0, 0
	v_add3_u32 v35, v35, v36, v37
	v_add_u32_e32 v0, 0x1000, v43
	v_lshl_add_u64 v[34:35], v[34:35], 1, v[44:45]
	v_ashrrev_i32_e32 v0, 5, v0
	s_waitcnt lgkmcnt(0)
; #define RTID opaque_tid()
; __device__ __forceinline__ void phase_win(const Params& p, int part, u16* smem, volatile LAS unsigned* vb_) {
;     ...
;     const int tid2 = RTID;
; #pragma unroll
;     for (int k = 0; k < 16; ++k) {
;       const int c = tid2 + 512 * k;
;       const int row = c >> 5, ch = c & 31;
;       const uint4 v = *(const uint4*)(smem + row * 264 + ch * 8);
;       u16* d_ = (ch < 16) ? dstA : dstB;
;       const int l_ = (ch < 16) ? ldA : ldB;
;       *(uint4*)(d_ + (size_t)(mt * 256 + row) * l_ + (ch & 15) * 8) = v;
;     }
;     __syncthreads();
;   }
	global_store_dwordx4 v[34:35], v[38:41], off
	v_mad_u64_u32 v[34:35], s[12:13], v0, s2, v[42:43]
	v_add_u32_e32 v0, s10, v0
	ds_read_b128 v[34:37], v34
	v_ashrrev_i32_e32 v38, 31, v0
	v_mul_lo_u32 v40, s0, v38
	v_mul_lo_u32 v41, s1, v0
	v_mad_u64_u32 v[38:39], s[12:13], s0, v0, 0
	v_add_u32_e32 v0, 0x1200, v43
	v_add3_u32 v39, v39, v40, v41
	v_ashrrev_i32_e32 v0, 5, v0
	v_lshl_add_u64 v[46:47], v[38:39], 1, v[44:45]
	v_mad_u64_u32 v[38:39], s[12:13], v0, s2, v[42:43]
	ds_read_b128 v[38:41], v38
	v_add_u32_e32 v0, s10, v0
	s_waitcnt lgkmcnt(1)
	global_store_dwordx4 v[46:47], v[34:37], off
	s_nop 1
	v_ashrrev_i32_e32 v34, 31, v0
	v_mul_lo_u32 v36, s0, v34
	v_mul_lo_u32 v37, s1, v0
	v_mad_u64_u32 v[34:35], s[12:13], s0, v0, 0
	v_add3_u32 v35, v35, v36, v37
	v_add_u32_e32 v0, 0x1400, v43
	v_lshl_add_u64 v[34:35], v[34:35], 1, v[44:45]
	v_ashrrev_i32_e32 v0, 5, v0
	s_waitcnt lgkmcnt(0)
	global_store_dwordx4 v[34:35], v[38:41], off
	v_mad_u64_u32 v[34:35], s[12:13], v0, s2, v[42:43]
	v_add_u32_e32 v0, s10, v0
	ds_read_b128 v[34:37], v34
	v_ashrrev_i32_e32 v38, 31, v0
	v_mul_lo_u32 v40, s0, v38
	v_mul_lo_u32 v41, s1, v0
	v_mad_u64_u32 v[38:39], s[12:13], s0, v0, 0
	v_add_u32_e32 v0, 0x1600, v43
	v_add3_u32 v39, v39, v40, v41
	v_ashrrev_i32_e32 v0, 5, v0
	v_lshl_add_u64 v[46:47], v[38:39], 1, v[44:45]
	v_mad_u64_u32 v[38:39], s[12:13], v0, s2, v[42:43]
	ds_read_b128 v[38:41], v38
	v_add_u32_e32 v0, s10, v0
	s_waitcnt lgkmcnt(1)
	global_store_dwordx4 v[46:47], v[34:37], off
	s_nop 1
	v_ashrrev_i32_e32 v34, 31, v0
	v_mul_lo_u32 v36, s0, v34
	v_mul_lo_u32 v37, s1, v0
	v_mad_u64_u32 v[34:35], s[12:13], s0, v0, 0
	v_add3_u32 v35, v35, v36, v37
	v_add_u32_e32 v0, 0x1800, v43
	v_lshl_add_u64 v[34:35], v[34:35], 1, v[44:45]
	v_ashrrev_i32_e32 v0, 5, v0
	s_waitcnt lgkmcnt(0)
	global_store_dwordx4 v[34:35], v[38:41], off
	v_mad_u64_u32 v[34:35], s[12:13], v0, s2, v[42:43]
	v_add_u32_e32 v0, s10, v0
	ds_read_b128 v[34:37], v34
	v_ashrrev_i32_e32 v38, 31, v0
	v_mul_lo_u32 v40, s0, v38
	v_mul_lo_u32 v41, s1, v0
	v_mad_u64_u32 v[38:39], s[12:13], s0, v0, 0
	v_add_u32_e32 v0, 0x1a00, v43
	v_add3_u32 v39, v39, v40, v41
	v_ashrrev_i32_e32 v0, 5, v0
	v_lshl_add_u64 v[46:47], v[38:39], 1, v[44:45]
	v_mad_u64_u32 v[38:39], s[12:13], v0, s2, v[42:43]
	ds_read_b128 v[38:41], v38
	v_add_u32_e32 v0, s10, v0
	s_waitcnt lgkmcnt(1)
	global_store_dwordx4 v[46:47], v[34:37], off
	s_nop 1
	v_ashrrev_i32_e32 v34, 31, v0
	v_mul_lo_u32 v36, s0, v34
	v_mul_lo_u32 v37, s1, v0
	v_mad_u64_u32 v[34:35], s[12:13], s0, v0, 0
	v_add3_u32 v35, v35, v36, v37
	v_add_u32_e32 v0, 0x1c00, v43
	v_lshl_add_u64 v[34:35], v[34:35], 1, v[44:45]
	v_ashrrev_i32_e32 v0, 5, v0
	s_waitcnt lgkmcnt(0)
	global_store_dwordx4 v[34:35], v[38:41], off
	v_mad_u64_u32 v[34:35], s[12:13], v0, s2, v[42:43]
	v_add_u32_e32 v0, s10, v0
	ds_read_b128 v[34:37], v34
	v_ashrrev_i32_e32 v38, 31, v0
	v_mul_lo_u32 v40, s0, v38
	v_mul_lo_u32 v41, s1, v0
	v_mad_u64_u32 v[38:39], s[12:13], s0, v0, 0
	v_add_u32_e32 v0, 0x1e00, v43
	v_add3_u32 v39, v39, v40, v41
	v_ashrrev_i32_e32 v0, 5, v0
	v_lshl_add_u64 v[46:47], v[38:39], 1, v[44:45]
	v_mad_u64_u32 v[38:39], s[12:13], v0, s2, v[42:43]
	ds_read_b128 v[38:41], v38
	v_add_u32_e32 v0, s10, v0
	s_waitcnt lgkmcnt(1)
	global_store_dwordx4 v[46:47], v[34:37], off
	s_mov_b64 s[12:13], -1
	s_nop 0
	v_ashrrev_i32_e32 v34, 31, v0
	v_mul_lo_u32 v36, s0, v34
	v_mul_lo_u32 v37, s1, v0
	v_mad_u64_u32 v[34:35], s[0:1], s0, v0, 0
	v_add3_u32 v35, v35, v36, v37
	v_lshl_add_u64 v[34:35], v[34:35], 1, v[44:45]
	s_waitcnt lgkmcnt(0)
	global_store_dwordx4 v[34:35], v[38:41], off
	s_barrier
	s_cbranch_vccz .LBB0_441
.LBB0_472:
	s_waitcnt vmcnt(0)
	s_setprio 0
	s_mov_b64 s[12:13], 0

; template <int MI, int NJ> ...
;   const int lane = tid & 63, wave = tid >> 6;
;   const int wm = wave >> 2, wn = wave & 3;
;   constexpr int AROWS = 32 * MI;
;   constexpr int BROWS = 64 * NJ;
;   u16* sA = smem;
;   u16* sB = smem + 2 * AROWS * 64;
;   const int lrow = tid >> 3, lkc = tid & 7;
;   const u16* Ag = A + (size_t)(row0 + lrow) * lda + kbeg + lkc * 8;
;   const u16* Bg = Bt + (size_t)(col0 + lrow) * ldb + kbeg + lkc * 8;
;   const size_t a64 = (size_t)64 * lda, b64 = (size_t)64 * ldb;
;   const int nk = (kend - kbeg) >> 6;
;   const long long nAoff = (long long)(nrow0 - row0) * lda + (nkbeg - kbeg);
;   const long long nBoff = (long long)(ncol0 - col0) * ldb + (nkbeg - kbeg);
;   u16* wa = sA + lrow * 64 + ((lkc ^ (lrow & 7)) * 8);
;   u16* wb = sB + lrow * 64 + ((lkc ^ (lrow & 7)) * 8);
;     ...
;   if (!pre) G8LOADP(Ag, Bg);
;   G8STORE(0);
;   {
;     const u16* ga_ = (1 < nk) ? Ag + 64 : Ag + nAoff;
;     const u16* gb_ = (1 < nk) ? Bg + 64 : Bg + nBoff;
;     G8LOADP(ga_, gb_);
;   }
;   __syncthreads();
;   const int sw0 = ((lane >> 4) ^ (lane & 7)) * 8;
;   const int dsw = (sw0 ^ 32) - sw0;
;   const u16* ra_ = sA + (wm * (16 * MI) + (lane & 15)) * 64 + sw0;
;   const u16* rb_ = sB + (wn * (16 * NJ) + (lane & 15)) * 64 + sw0;
.LBB0_475:
	s_nop 0
	v_readlane_b32 s0, v255, 4
	v_readlane_b32 s1, v255, 5
	s_and_b64 vcc, exec, s[0:1]
	s_cbranch_vccz .LBB0_484
	s_waitcnt vmcnt(15)
	v_mov_b32_e32 v2, v175
	ds_read_b32 v0, v230
	s_waitcnt lgkmcnt(0)
	v_readfirstlane_b32 s0, v0
	s_ashr_i32 s37, s0, 3
	s_cmp_gt_i32 s37, 31
	s_cbranch_scc1 .LBB0_483
	s_cmp_eq_u32 s82, 10
	s_movk_i32 s1, 0xb00
	s_cselect_b32 s10, 0x400, s1
	s_mov_b32 s1, 0x3810000
	s_cselect_b32 s1, s1, 0x5810000
	s_cmp_eq_u32 s82, 1
	s_mov_b32 s11, 0xb00000
	s_cselect_b32 s11, s11, 0x1b80000
	s_cmp_eq_u32 s82, 10
	s_mov_b32 s12, 0xf010000
	s_cselect_b32 s12, s12, 0xb010000
	s_cselect_b32 s13, 0x3400000, s11
	s_add_u32 s11, s72, s12
	s_addc_u32 s20, s73, 0
	s_add_u32 s12, s72, s13
	s_addc_u32 s13, s73, 0
	s_add_u32 s38, s72, s1
	v_lshlrev_b32_e32 v0, 4, v2
	s_addc_u32 s39, s73, 0
	v_ashrrev_i32_e32 v184, 3, v2
	v_and_b32_e32 v0, 0x70, v0
	v_and_b32_e32 v234, 7, v184
	s_lshl_b32 s48, s10, 1
	s_lshl_b32 s49, s10, 7
	v_mul_lo_u32 v234, v234, s48
	v_add_u32_e32 v234, v234, v0
	v_add_u32_e32 v235, s49, v234
	v_add_u32_e32 v236, s49, v235
	v_add_u32_e32 v237, s49, v236
	v_cmp_lt_u32_e32 vcc, 0xff, v175
	s_cbranch_vccz .Lprio_skip_gf32
	s_setprio 1
.Lprio_skip_gf32:
	v_lshl_add_u64 v[176:177], s[38:39], 0, v[0:1]
	v_lshl_add_u64 v[178:179], s[12:13], 0, v[0:1]
	v_xor_b32_e32 v0, v184, v2
	v_lshlrev_b32_e32 v0, 4, v0
	v_and_b32_e32 v0, 0x70, v0
	v_lshl_or_b32 v185, v184, 7, v0
	v_lshrrev_b32_e32 v0, 4, v2
	v_and_b32_e32 v3, 7, v2
	v_bitop3_b32 v0, v0, v3, 3 bitop3:0x6c
	v_lshlrev_b32_e32 v3, 3, v0
	v_xor_b32_e32 v4, 32, v3
	v_sub_u32_e32 v3, v4, v3
	v_ashrrev_i32_e32 v4, 1, v2
	v_and_b32_e32 v4, 0xffffff80, v4
	v_and_or_b32 v5, v2, 15, v4
	v_lshlrev_b32_e32 v0, 4, v0
	s_lshl_b32 s0, s0, 3
	v_lshl_or_b32 v187, v5, 7, v0
	v_lshlrev_b32_e32 v5, 7, v2
	s_and_b32 s22, s0, 56
	v_and_b32_e32 v5, 0x6780, v5
	s_mov_b32 s0, 0x10000
	v_or3_b32 v188, v5, v0, s0
	v_lshrrev_b32_e32 v0, 2, v2
	v_and_or_b32 v0, v0, 12, v4
	v_and_b32_e32 v2, 0xcf, v2
	v_mul_lo_u32 v0, v0, s2
	s_lshl_b32 s23, s10, 6
	v_lshl_add_u32 v189, v2, 1, v0
	v_mov_b32_e32 v0, v1
	s_lshr_b32 s21, s10, 6
	v_add_u32_e32 v186, 0x10000, v185
	s_lshl_b32 s0, s10, 7
	s_mov_b32 s1, s59
	s_mov_b64 s[12:13], 0
	s_lshl_b32 s58, s23, 1
	v_lshlrev_b32_e32 v190, 1, v3
	s_waitcnt vmcnt(6)
	v_mov_b64_e32 v[42:43], v[0:1]
	v_mov_b64_e32 v[44:45], v[0:1]
	v_mov_b64_e32 v[62:63], v[0:1]
	v_mov_b64_e32 v[64:65], v[0:1]
	v_mov_b64_e32 v[74:75], v[0:1]
	v_mov_b64_e32 v[76:77], v[0:1]

; template <int MI, int NJ> ...
;     ...
;   for (int kt = 0; kt < nk; ++kt) {
;     const int buf = kt & 1;
;     {
;       G8STORE(buf ^ 1);
;       const u16* ga_ = (kt + 2 < nk) ? Ag + (kt + 2) * 64 : Ag + nAoff;
;       const u16* gb_ = (kt + 2 < nk) ? Bg + (kt + 2) * 64 : Bg + nBoff;
;       G8LOADP(ga_, gb_);
;     }
;     __builtin_amdgcn_sched_barrier(0);
;     __builtin_amdgcn_s_setprio(1);
;     const u16* a = ra_ + buf * AROWS * 64;
;     const u16* b = rb_ + buf * BROWS * 64;
; #pragma unroll
;     for (int ks = 0; ks < 2; ++ks) {
;       const u16* a_ = ks ? a + dsw : a;
;       const u16* b_ = ks ? b + dsw : b;
;       bf16x8 bfr[NJ];
; #pragma unroll
;       for (int j = 0; j < NJ; ++j) bfr[j] = *(const bf16x8*)(b_ + j * 16 * 64);
; #pragma unroll
;       for (int ih = 0; ih < MI / 4; ++ih) {
;         bf16x8 af[4];
; #pragma unroll
;         for (int i = 0; i < 4; ++i) af[i] = *(const bf16x8*)(a_ + (ih * 4 + i) * 16 * 64);
; #pragma unroll
;         for (int i = 0; i < 4; ++i)
; #pragma unroll
;           for (int j = 0; j < NJ; ++j) acc[ih * 4 + i][j] = mfma16(af[i], bfr[j], acc[ih * 4 + i][j]);
;       }
;     }
;     __builtin_amdgcn_s_setprio(0);
;     __builtin_amdgcn_sched_barrier(0);
;     __syncthreads();
;   }
.LBB0_481:
	s_waitcnt lgkmcnt(6)
	v_mfma_f32_16x16x32_bf16 v[158:161], v[166:169], v[162:165], v[158:161]
	s_waitcnt lgkmcnt(5)
	v_mfma_f32_16x16x32_bf16 v[154:157], v[170:173], v[162:165], v[154:157]
	s_waitcnt lgkmcnt(4)
	v_mfma_f32_16x16x32_bf16 v[150:153], v[192:195], v[162:165], v[150:153]
	s_waitcnt lgkmcnt(3)
	v_mfma_f32_16x16x32_bf16 v[146:149], v[196:199], v[162:165], v[146:149]
	ds_read_b128 v[162:165], v0 offset:8192
	s_waitcnt lgkmcnt(3)
	v_mfma_f32_16x16x32_bf16 v[142:145], v[166:169], v[204:207], v[142:145]
	v_mfma_f32_16x16x32_bf16 v[138:141], v[170:173], v[204:207], v[138:141]
	v_mfma_f32_16x16x32_bf16 v[134:137], v[192:195], v[204:207], v[134:137]
	v_mfma_f32_16x16x32_bf16 v[130:133], v[196:199], v[204:207], v[130:133]
	ds_read_b128 v[204:207], v0 offset:10240
	s_waitcnt lgkmcnt(3)
	v_mfma_f32_16x16x32_bf16 v[126:129], v[166:169], v[208:211], v[126:129]
	v_mfma_f32_16x16x32_bf16 v[122:125], v[170:173], v[208:211], v[122:125]
	v_mfma_f32_16x16x32_bf16 v[118:121], v[192:195], v[208:211], v[118:121]
	v_mfma_f32_16x16x32_bf16 v[114:117], v[196:199], v[208:211], v[114:117]
	ds_read_b128 v[208:211], v0 offset:12288
	ds_read_b128 v[212:215], v191
	ds_read_b128 v[216:219], v191 offset:2048
	s_waitcnt lgkmcnt(5)
	v_mfma_f32_16x16x32_bf16 v[110:113], v[166:169], v[238:241], v[110:113]
	v_mfma_f32_16x16x32_bf16 v[106:109], v[170:173], v[238:241], v[106:109]
	v_mfma_f32_16x16x32_bf16 v[102:105], v[192:195], v[238:241], v[102:105]
	v_mfma_f32_16x16x32_bf16 v[98:101], v[196:199], v[238:241], v[98:101]
	ds_read_b128 v[238:241], v0 offset:14336
	ds_read_b128 v[220:223], v191 offset:4096
	ds_read_b128 v[224:227], v191 offset:6144
	s_waitcnt lgkmcnt(7)
	v_mfma_f32_16x16x32_bf16 v[94:97], v[166:169], v[162:165], v[94:97]
	v_mfma_f32_16x16x32_bf16 v[90:93], v[170:173], v[162:165], v[90:93]
	v_mfma_f32_16x16x32_bf16 v[86:89], v[192:195], v[162:165], v[86:89]
	v_mfma_f32_16x16x32_bf16 v[82:85], v[196:199], v[162:165], v[82:85]
	v_add_u32_e32 v0, v0, v190
	ds_read_b128 v[162:165], v0
	s_waitcnt vmcnt(7)
	ds_write_b128 v228, v[10:13]
	global_load_dwordx4 v[10:13], v234, s[50:51]
	s_waitcnt lgkmcnt(8)
	v_mfma_f32_16x16x32_bf16 v[78:81], v[166:169], v[204:207], v[78:81]
	v_mfma_f32_16x16x32_bf16 v[70:73], v[170:173], v[204:207], v[70:73]
	v_mfma_f32_16x16x32_bf16 v[66:69], v[192:195], v[204:207], v[66:69]
	v_mfma_f32_16x16x32_bf16 v[58:61], v[196:199], v[204:207], v[58:61]
	ds_read_b128 v[204:207], v0 offset:2048
	s_waitcnt vmcnt(7)
	ds_write_b128 v228, v[2:5] offset:8192
	global_load_dwordx4 v[2:5], v235, s[50:51]
	s_waitcnt lgkmcnt(9)
	v_mfma_f32_16x16x32_bf16 v[54:57], v[166:169], v[208:211], v[54:57]
	v_mfma_f32_16x16x32_bf16 v[50:53], v[170:173], v[208:211], v[50:53]
	v_mfma_f32_16x16x32_bf16 v[46:49], v[192:195], v[208:211], v[46:49]
	v_mfma_f32_16x16x32_bf16 v[38:41], v[196:199], v[208:211], v[38:41]
	ds_read_b128 v[208:211], v0 offset:4096
	s_waitcnt vmcnt(7)
	ds_write_b128 v228, v[6:9] offset:16384
	global_load_dwordx4 v[6:9], v236, s[50:51]
	s_waitcnt lgkmcnt(8)
	v_mfma_f32_16x16x32_bf16 v[34:37], v[166:169], v[238:241], v[34:37]
	v_mfma_f32_16x16x32_bf16 v[30:33], v[170:173], v[238:241], v[30:33]
	v_mfma_f32_16x16x32_bf16 v[26:29], v[192:195], v[238:241], v[26:29]
	v_mfma_f32_16x16x32_bf16 v[22:25], v[196:199], v[238:241], v[22:25]
	ds_read_b128 v[238:241], v0 offset:6144
	s_waitcnt vmcnt(7)
	ds_write_b128 v228, v[14:17] offset:24576
	global_load_dwordx4 v[14:17], v237, s[50:51]
	s_waitcnt lgkmcnt(7)
	v_mfma_f32_16x16x32_bf16 v[158:161], v[212:215], v[162:165], v[158:161]
	v_mfma_f32_16x16x32_bf16 v[154:157], v[216:219], v[162:165], v[154:157]
	v_mfma_f32_16x16x32_bf16 v[150:153], v[220:223], v[162:165], v[150:153]
	v_mfma_f32_16x16x32_bf16 v[146:149], v[224:227], v[162:165], v[146:149]
	ds_read_b128 v[162:165], v0 offset:8192
	s_waitcnt vmcnt(7)
	ds_write_b128 v229, v[18:21]
	global_load_dwordx4 v[18:21], v234, s[52:53]
	s_waitcnt lgkmcnt(7)
	v_mfma_f32_16x16x32_bf16 v[142:145], v[212:215], v[204:207], v[142:145]
	v_mfma_f32_16x16x32_bf16 v[138:141], v[216:219], v[204:207], v[138:141]
	v_mfma_f32_16x16x32_bf16 v[134:137], v[220:223], v[204:207], v[134:137]
	v_mfma_f32_16x16x32_bf16 v[130:133], v[224:227], v[204:207], v[130:133]
	ds_read_b128 v[204:207], v0 offset:10240
	s_waitcnt vmcnt(7)
	ds_write_b128 v229, v[42:45] offset:8192
	global_load_dwordx4 v[42:45], v235, s[52:53]
	s_waitcnt lgkmcnt(7)
	v_mfma_f32_16x16x32_bf16 v[126:129], v[212:215], v[208:211], v[126:129]
	v_mfma_f32_16x16x32_bf16 v[122:125], v[216:219], v[208:211], v[122:125]
	v_mfma_f32_16x16x32_bf16 v[118:121], v[220:223], v[208:211], v[118:121]
	v_mfma_f32_16x16x32_bf16 v[114:117], v[224:227], v[208:211], v[114:117]
	ds_read_b128 v[208:211], v0 offset:12288
	s_waitcnt vmcnt(7)
	ds_write_b128 v229, v[62:65] offset:16384
	global_load_dwordx4 v[62:65], v236, s[52:53]
	s_waitcnt lgkmcnt(7)
	v_mfma_f32_16x16x32_bf16 v[110:113], v[212:215], v[238:241], v[110:113]
	v_mfma_f32_16x16x32_bf16 v[106:109], v[216:219], v[238:241], v[106:109]
	v_mfma_f32_16x16x32_bf16 v[102:105], v[220:223], v[238:241], v[102:105]
	v_mfma_f32_16x16x32_bf16 v[98:101], v[224:227], v[238:241], v[98:101]
	ds_read_b128 v[238:241], v0 offset:14336
	s_waitcnt vmcnt(7)
	ds_write_b128 v229, v[74:77] offset:24576
	global_load_dwordx4 v[74:77], v237, s[52:53]
	s_waitcnt lgkmcnt(7)
	v_mfma_f32_16x16x32_bf16 v[94:97], v[212:215], v[162:165], v[94:97]
	v_mfma_f32_16x16x32_bf16 v[90:93], v[216:219], v[162:165], v[90:93]
	v_mfma_f32_16x16x32_bf16 v[86:89], v[220:223], v[162:165], v[86:89]
	v_mfma_f32_16x16x32_bf16 v[82:85], v[224:227], v[162:165], v[82:85]
	s_waitcnt lgkmcnt(0)
	s_barrier
; template <int MI, int NJ> ...
;     ...
;     const u16* a = ra_ + buf * AROWS * 64;
;     const u16* b = rb_ + buf * BROWS * 64;
; #pragma unroll
;     for (int ks = 0; ks < 2; ++ks) {
;       const u16* a_ = ks ? a + dsw : a;
;       const u16* b_ = ks ? b + dsw : b;
;       bf16x8 bfr[NJ];
; #pragma unroll
;       for (int j = 0; j < NJ; ++j) bfr[j] = *(const bf16x8*)(b_ + j * 16 * 64);
; #pragma unroll
;       for (int ih = 0; ih < MI / 4; ++ih) {
;         bf16x8 af[4];
; #pragma unroll
;         for (int i = 0; i < 4; ++i) af[i] = *(const bf16x8*)(a_ + (ih * 4 + i) * 16 * 64);
; #pragma unroll
;         for (int i = 0; i < 4; ++i)
; #pragma unroll
;           for (int j = 0; j < NJ; ++j) acc[ih * 4 + i][j] = mfma16(af[i], bfr[j], acc[ih * 4 + i][j]);
;       }
;     }
; __device__ __forceinline__ void phase_gemm_f32(const u16* A, const u16* Bt, int K, u16* out, u16* smem,
;                                                volatile LAS unsigned* vb_) {
;     ...
; #pragma unroll
;     for (int i = 0; i < 8; ++i)
; #pragma unroll
;       for (int j = 0; j < 4; ++j)
; #pragma unroll
;         for (int r = 0; r < 4; ++r)
;           smem[(wm * 128 + i * 16 + (lane >> 4) * 4 + r) * 264 + wn * 64 + j * 16 + (lane & 15)] = f2bf(acc[i][j][r]);
;     __syncthreads();
	s_add_i32 s44, s44, 1
	s_add_i32 s39, s39, 64
	s_addk_i32 s43, 0x4000
	s_and_b32 s45, s43, 0x4000
	s_xor_b32 s46, s45, 0x4000
	s_lshl_b32 s46, s46, 1
	v_add_u32_e32 v228, s46, v185
	v_add_u32_e32 v229, s46, v186
	s_add_i32 s46, s44, 2
	s_cmp_lt_u32 s46, s21
	s_cselect_b32 s47, 0, s12
	s_cselect_b32 s46, s39, s13
	s_cselect_b32 s49, 0, s37
	s_cselect_b32 s48, s39, s38
	s_lshl_b64 s[46:47], s[46:47], 1
	s_lshl_b64 s[48:49], s[48:49], 1
	s_add_u32 s50, s62, s46
	s_addc_u32 s51, s63, s47
	s_add_u32 s52, s64, s48
	s_addc_u32 s53, s65, s49
	s_lshl_b32 s45, s45, 1
	v_add_u32_e32 v0, s45, v187
	v_add_u32_e32 v191, s45, v188
	ds_read_b128 v[166:169], v191
	ds_read_b128 v[162:165], v0
	ds_read_b128 v[170:173], v191 offset:2048
	ds_read_b128 v[192:195], v191 offset:4096
	ds_read_b128 v[196:199], v191 offset:6144
	v_mfma_f32_16x16x32_bf16 v[78:81], v[212:215], v[204:207], v[78:81]
	v_mfma_f32_16x16x32_bf16 v[70:73], v[216:219], v[204:207], v[70:73]
	v_mfma_f32_16x16x32_bf16 v[66:69], v[220:223], v[204:207], v[66:69]
	v_mfma_f32_16x16x32_bf16 v[58:61], v[224:227], v[204:207], v[58:61]
	ds_read_b128 v[204:207], v0 offset:2048
	v_mfma_f32_16x16x32_bf16 v[54:57], v[212:215], v[208:211], v[54:57]
	v_mfma_f32_16x16x32_bf16 v[50:53], v[216:219], v[208:211], v[50:53]
	v_mfma_f32_16x16x32_bf16 v[46:49], v[220:223], v[208:211], v[46:49]
	v_mfma_f32_16x16x32_bf16 v[38:41], v[224:227], v[208:211], v[38:41]
	ds_read_b128 v[208:211], v0 offset:4096
	v_mfma_f32_16x16x32_bf16 v[34:37], v[212:215], v[238:241], v[34:37]
	v_mfma_f32_16x16x32_bf16 v[30:33], v[216:219], v[238:241], v[30:33]
	v_mfma_f32_16x16x32_bf16 v[26:29], v[220:223], v[238:241], v[26:29]
	v_mfma_f32_16x16x32_bf16 v[22:25], v[224:227], v[238:241], v[22:25]
	ds_read_b128 v[238:241], v0 offset:6144
	v_add_u32_e32 v191, v191, v190
	s_cmp_lg_u32 s21, s44
	s_cbranch_scc1 .LBB0_481
	v_and_b32_e32 v228, 15, v175
	v_bfe_u32 v229, v175, 8, 1
	v_lshl_or_b32 v228, v229, 7, v228
	v_mul_u32_u24_e32 v228, 0x210, v228
	v_bfe_u32 v229, v175, 6, 2
	v_lshl_add_u32 v228, v229, 7, v228
	v_bfe_u32 v229, v175, 4, 2
	v_lshl_add_u32 v228, v229, 3, v228
	v_cvt_pk_bf16_f32 v158, v158, v159
	v_cvt_pk_bf16_f32 v159, v160, v161
	v_cvt_pk_bf16_f32 v154, v154, v155
	v_cvt_pk_bf16_f32 v155, v156, v157
	v_cvt_pk_bf16_f32 v150, v150, v151
	v_cvt_pk_bf16_f32 v151, v152, v153
	v_cvt_pk_bf16_f32 v146, v146, v147
	v_cvt_pk_bf16_f32 v147, v148, v149
	ds_write_b64 v228, v[158:159]
	ds_write_b64 v228, v[154:155] offset:32
	ds_write_b64 v228, v[150:151] offset:64
	ds_write_b64 v228, v[146:147] offset:96
	v_cvt_pk_bf16_f32 v142, v142, v143
	v_cvt_pk_bf16_f32 v143, v144, v145
	v_cvt_pk_bf16_f32 v138, v138, v139
	v_cvt_pk_bf16_f32 v139, v140, v141
	v_cvt_pk_bf16_f32 v134, v134, v135
	v_cvt_pk_bf16_f32 v135, v136, v137
	v_cvt_pk_bf16_f32 v130, v130, v131
	v_cvt_pk_bf16_f32 v131, v132, v133
	ds_write_b64 v228, v[142:143] offset:8448
	ds_write_b64 v228, v[138:139] offset:8480
	ds_write_b64 v228, v[134:135] offset:8512
	ds_write_b64 v228, v[130:131] offset:8544
	v_cvt_pk_bf16_f32 v126, v126, v127
	v_cvt_pk_bf16_f32 v127, v128, v129
	v_cvt_pk_bf16_f32 v122, v122, v123
	v_cvt_pk_bf16_f32 v123, v124, v125
	v_cvt_pk_bf16_f32 v118, v118, v119
	v_cvt_pk_bf16_f32 v119, v120, v121
	v_cvt_pk_bf16_f32 v114, v114, v115
	v_cvt_pk_bf16_f32 v115, v116, v117
	ds_write_b64 v228, v[126:127] offset:16896
	ds_write_b64 v228, v[122:123] offset:16928
	ds_write_b64 v228, v[118:119] offset:16960
	ds_write_b64 v228, v[114:115] offset:16992
	v_cvt_pk_bf16_f32 v110, v110, v111
	v_cvt_pk_bf16_f32 v111, v112, v113
	v_cvt_pk_bf16_f32 v106, v106, v107
	v_cvt_pk_bf16_f32 v107, v108, v109
	v_cvt_pk_bf16_f32 v102, v102, v103
	v_cvt_pk_bf16_f32 v103, v104, v105
	v_cvt_pk_bf16_f32 v98, v98, v99
	v_cvt_pk_bf16_f32 v99, v100, v101
	ds_write_b64 v228, v[110:111] offset:25344
	ds_write_b64 v228, v[106:107] offset:25376
	ds_write_b64 v228, v[102:103] offset:25408
	ds_write_b64 v228, v[98:99] offset:25440
	v_cvt_pk_bf16_f32 v94, v94, v95
	v_cvt_pk_bf16_f32 v95, v96, v97
	v_cvt_pk_bf16_f32 v90, v90, v91
	v_cvt_pk_bf16_f32 v91, v92, v93
	v_cvt_pk_bf16_f32 v86, v86, v87
	v_cvt_pk_bf16_f32 v87, v88, v89
	v_cvt_pk_bf16_f32 v82, v82, v83
	v_cvt_pk_bf16_f32 v83, v84, v85
	ds_write_b64 v228, v[94:95] offset:33792
	ds_write_b64 v228, v[90:91] offset:33824
	ds_write_b64 v228, v[86:87] offset:33856
	ds_write_b64 v228, v[82:83] offset:33888
	v_cvt_pk_bf16_f32 v78, v78, v79
	v_cvt_pk_bf16_f32 v79, v80, v81
	v_cvt_pk_bf16_f32 v70, v70, v71
	v_cvt_pk_bf16_f32 v71, v72, v73
	v_cvt_pk_bf16_f32 v66, v66, v67
	v_cvt_pk_bf16_f32 v67, v68, v69
	v_cvt_pk_bf16_f32 v58, v58, v59
	v_cvt_pk_bf16_f32 v59, v60, v61
	ds_write_b64 v228, v[78:79] offset:42240
	ds_write_b64 v228, v[70:71] offset:42272
	ds_write_b64 v228, v[66:67] offset:42304
	ds_write_b64 v228, v[58:59] offset:42336
	v_cvt_pk_bf16_f32 v54, v54, v55
	v_cvt_pk_bf16_f32 v55, v56, v57
	v_cvt_pk_bf16_f32 v50, v50, v51
	v_cvt_pk_bf16_f32 v51, v52, v53
	v_cvt_pk_bf16_f32 v46, v46, v47
	v_cvt_pk_bf16_f32 v47, v48, v49
	v_cvt_pk_bf16_f32 v38, v38, v39
	v_cvt_pk_bf16_f32 v39, v40, v41
	ds_write_b64 v228, v[54:55] offset:50688
	ds_write_b64 v228, v[50:51] offset:50720
	ds_write_b64 v228, v[46:47] offset:50752
	ds_write_b64 v228, v[38:39] offset:50784
	v_cvt_pk_bf16_f32 v34, v34, v35
	v_cvt_pk_bf16_f32 v35, v36, v37
	v_cvt_pk_bf16_f32 v30, v30, v31
	v_cvt_pk_bf16_f32 v31, v32, v33
	v_cvt_pk_bf16_f32 v26, v26, v27
	v_cvt_pk_bf16_f32 v27, v28, v29
	v_cvt_pk_bf16_f32 v22, v22, v23
	v_cvt_pk_bf16_f32 v23, v24, v25
	ds_write_b64 v228, v[34:35] offset:59136
	ds_write_b64 v228, v[30:31] offset:59168
	ds_write_b64 v228, v[26:27] offset:59200
	ds_write_b64 v228, v[22:23] offset:59232
	s_ashr_i32 s43, s42, 31
	v_mov_b32_e32 v34, v175
	s_lshl_b64 s[12:13], s[42:43], 1
	s_waitcnt lgkmcnt(0)
	s_barrier
; #define RTID opaque_tid()
; __device__ __forceinline__ void phase_gemm_f32(const u16* A, const u16* Bt, int K, u16* out, u16* smem,
;                                                volatile LAS unsigned* vb_) {
;     ...
;     const int tid2 = RTID;
; #pragma unroll
;     for (int k = 0; k < 16; ++k) {
;       const int c = tid2 + 512 * k;
;       const int row = c >> 5, ch = c & 31;
;       const uint4 v = *(const uint4*)(smem + row * 264 + ch * 8);
;       *(uint4*)(out + (size_t)(mt * 256 + row) * 1024 + nt * 256 + ch * 8) = v;
;     }
;     __syncthreads();
;   }
	s_add_u32 s12, s11, s12
	v_lshlrev_b32_e32 v0, 4, v34
	v_and_b32_e32 v0, 0x1f0, v0
	s_addc_u32 s13, s20, s13
	v_ashrrev_i32_e32 v26, 5, v34
	v_lshl_add_u64 v[30:31], s[12:13], 0, v[0:1]
	v_mad_u64_u32 v[22:23], s[12:13], v26, s2, v[0:1]
	v_add_u32_e32 v26, s23, v26
	v_ashrrev_i32_e32 v27, 31, v26
	ds_read_b128 v[22:25], v22
	v_lshlrev_b64 v[26:27], 11, v[26:27]
	v_lshl_add_u64 v[32:33], v[30:31], 0, v[26:27]
	v_add_u32_e32 v26, 0x200, v34
	v_ashrrev_i32_e32 v35, 5, v26
	v_mad_u64_u32 v[26:27], s[12:13], v35, s2, v[0:1]
	ds_read_b128 v[26:29], v26
	s_waitcnt lgkmcnt(1)
	global_store_dwordx4 v[32:33], v[22:25], off
	s_and_b64 vcc, exec, s[40:41]
	s_mov_b32 s37, s36
	v_add_u32_e32 v22, s23, v35
	v_ashrrev_i32_e32 v23, 31, v22
	v_lshlrev_b64 v[22:23], 11, v[22:23]
	v_lshl_add_u64 v[22:23], v[30:31], 0, v[22:23]
	s_waitcnt lgkmcnt(0)
	global_store_dwordx4 v[22:23], v[26:29], off
	v_add_u32_e32 v22, 0x400, v34
	s_nop 0
	v_ashrrev_i32_e32 v26, 5, v22
	v_mad_u64_u32 v[22:23], s[12:13], v26, s2, v[0:1]
	v_add_u32_e32 v26, s23, v26
	v_ashrrev_i32_e32 v27, 31, v26
	ds_read_b128 v[22:25], v22
	v_lshlrev_b64 v[26:27], 11, v[26:27]
	v_lshl_add_u64 v[32:33], v[30:31], 0, v[26:27]
	v_add_u32_e32 v26, 0x600, v34
	v_ashrrev_i32_e32 v35, 5, v26
	v_mad_u64_u32 v[26:27], s[12:13], v35, s2, v[0:1]
	ds_read_b128 v[26:29], v26
	s_waitcnt lgkmcnt(1)
	global_store_dwordx4 v[32:33], v[22:25], off
	s_nop 1
	v_add_u32_e32 v22, s23, v35
	v_ashrrev_i32_e32 v23, 31, v22
	v_lshlrev_b64 v[22:23], 11, v[22:23]
	v_lshl_add_u64 v[22:23], v[30:31], 0, v[22:23]
	s_waitcnt lgkmcnt(0)
	global_store_dwordx4 v[22:23], v[26:29], off
	v_add_u32_e32 v22, 0x800, v34
	s_nop 0
	v_ashrrev_i32_e32 v26, 5, v22
	v_mad_u64_u32 v[22:23], s[12:13], v26, s2, v[0:1]
	v_add_u32_e32 v26, s23, v26
	v_ashrrev_i32_e32 v27, 31, v26
	ds_read_b128 v[22:25], v22
	v_lshlrev_b64 v[26:27], 11, v[26:27]
	v_lshl_add_u64 v[32:33], v[30:31], 0, v[26:27]
	v_add_u32_e32 v26, 0xa00, v34
	v_ashrrev_i32_e32 v35, 5, v26
	v_mad_u64_u32 v[26:27], s[12:13], v35, s2, v[0:1]
	ds_read_b128 v[26:29], v26
	s_waitcnt lgkmcnt(1)
	global_store_dwordx4 v[32:33], v[22:25], off
	s_nop 1
	v_add_u32_e32 v22, s23, v35
	v_ashrrev_i32_e32 v23, 31, v22
	v_lshlrev_b64 v[22:23], 11, v[22:23]
	v_lshl_add_u64 v[22:23], v[30:31], 0, v[22:23]
	s_waitcnt lgkmcnt(0)
	global_store_dwordx4 v[22:23], v[26:29], off
	v_add_u32_e32 v22, 0xc00, v34
	s_nop 0
	v_ashrrev_i32_e32 v26, 5, v22
	v_mad_u64_u32 v[22:23], s[12:13], v26, s2, v[0:1]
	v_add_u32_e32 v26, s23, v26
	v_ashrrev_i32_e32 v27, 31, v26
	ds_read_b128 v[22:25], v22
	v_lshlrev_b64 v[26:27], 11, v[26:27]
	v_lshl_add_u64 v[32:33], v[30:31], 0, v[26:27]
	v_add_u32_e32 v26, 0xe00, v34
	v_ashrrev_i32_e32 v35, 5, v26
	v_mad_u64_u32 v[26:27], s[12:13], v35, s2, v[0:1]
	ds_read_b128 v[26:29], v26
	s_waitcnt lgkmcnt(1)
	global_store_dwordx4 v[32:33], v[22:25], off
	s_nop 1
	v_add_u32_e32 v22, s23, v35
	v_ashrrev_i32_e32 v23, 31, v22
	v_lshlrev_b64 v[22:23], 11, v[22:23]
	v_lshl_add_u64 v[22:23], v[30:31], 0, v[22:23]
	s_waitcnt lgkmcnt(0)
	global_store_dwordx4 v[22:23], v[26:29], off
	v_add_u32_e32 v22, 0x1000, v34
	s_nop 0
	v_ashrrev_i32_e32 v26, 5, v22
	v_mad_u64_u32 v[22:23], s[12:13], v26, s2, v[0:1]
	v_add_u32_e32 v26, s23, v26
	v_ashrrev_i32_e32 v27, 31, v26
	ds_read_b128 v[22:25], v22
	v_lshlrev_b64 v[26:27], 11, v[26:27]
	v_lshl_add_u64 v[32:33], v[30:31], 0, v[26:27]
	v_add_u32_e32 v26, 0x1200, v34
	v_ashrrev_i32_e32 v35, 5, v26
	v_mad_u64_u32 v[26:27], s[12:13], v35, s2, v[0:1]
	ds_read_b128 v[26:29], v26
	s_waitcnt lgkmcnt(1)
	global_store_dwordx4 v[32:33], v[22:25], off
	s_nop 1
	v_add_u32_e32 v22, s23, v35
	v_ashrrev_i32_e32 v23, 31, v22
	v_lshlrev_b64 v[22:23], 11, v[22:23]
	v_lshl_add_u64 v[22:23], v[30:31], 0, v[22:23]
	s_waitcnt lgkmcnt(0)
	global_store_dwordx4 v[22:23], v[26:29], off
	v_add_u32_e32 v22, 0x1400, v34
	s_nop 0
	v_ashrrev_i32_e32 v26, 5, v22
	v_mad_u64_u32 v[22:23], s[12:13], v26, s2, v[0:1]
	v_add_u32_e32 v26, s23, v26
	v_ashrrev_i32_e32 v27, 31, v26
	ds_read_b128 v[22:25], v22
	v_lshlrev_b64 v[26:27], 11, v[26:27]
	v_lshl_add_u64 v[32:33], v[30:31], 0, v[26:27]
	v_add_u32_e32 v26, 0x1600, v34
	v_ashrrev_i32_e32 v35, 5, v26
	v_mad_u64_u32 v[26:27], s[12:13], v35, s2, v[0:1]
	ds_read_b128 v[26:29], v26
	s_waitcnt lgkmcnt(1)
	global_store_dwordx4 v[32:33], v[22:25], off
	s_nop 1
	v_add_u32_e32 v22, s23, v35
	v_ashrrev_i32_e32 v23, 31, v22
	v_lshlrev_b64 v[22:23], 11, v[22:23]
	v_lshl_add_u64 v[22:23], v[30:31], 0, v[22:23]
	s_waitcnt lgkmcnt(0)
	global_store_dwordx4 v[22:23], v[26:29], off
	v_add_u32_e32 v22, 0x1800, v34
	s_nop 0
	v_ashrrev_i32_e32 v26, 5, v22
	v_mad_u64_u32 v[22:23], s[12:13], v26, s2, v[0:1]
	v_add_u32_e32 v26, s23, v26
	v_ashrrev_i32_e32 v27, 31, v26
	ds_read_b128 v[22:25], v22
	v_lshlrev_b64 v[26:27], 11, v[26:27]
	v_lshl_add_u64 v[32:33], v[30:31], 0, v[26:27]
	v_add_u32_e32 v26, 0x1a00, v34
	v_ashrrev_i32_e32 v35, 5, v26
	v_mad_u64_u32 v[26:27], s[12:13], v35, s2, v[0:1]
	ds_read_b128 v[26:29], v26
	s_waitcnt lgkmcnt(1)
	global_store_dwordx4 v[32:33], v[22:25], off
	s_nop 1
	v_add_u32_e32 v22, s23, v35
	v_ashrrev_i32_e32 v23, 31, v22
	v_lshlrev_b64 v[22:23], 11, v[22:23]
	v_lshl_add_u64 v[22:23], v[30:31], 0, v[22:23]
	s_waitcnt lgkmcnt(0)
	global_store_dwordx4 v[22:23], v[26:29], off
	v_add_u32_e32 v22, 0x1c00, v34
	s_nop 0
	v_ashrrev_i32_e32 v26, 5, v22
	v_mad_u64_u32 v[22:23], s[12:13], v26, s2, v[0:1]
	v_add_u32_e32 v26, s23, v26
	v_ashrrev_i32_e32 v27, 31, v26
	ds_read_b128 v[22:25], v22
	v_lshlrev_b64 v[26:27], 11, v[26:27]
	v_lshl_add_u64 v[32:33], v[30:31], 0, v[26:27]
	v_add_u32_e32 v26, 0x1e00, v34
	v_ashrrev_i32_e32 v34, 5, v26
	v_mad_u64_u32 v[26:27], s[12:13], v34, s2, v[0:1]
	ds_read_b128 v[26:29], v26
	s_waitcnt lgkmcnt(1)
	global_store_dwordx4 v[32:33], v[22:25], off
	s_mov_b64 s[12:13], -1
	s_nop 0
	v_add_u32_e32 v22, s23, v34
	v_ashrrev_i32_e32 v23, 31, v22
	v_lshlrev_b64 v[22:23], 11, v[22:23]
	v_lshl_add_u64 v[22:23], v[30:31], 0, v[22:23]
	s_waitcnt lgkmcnt(0)
	global_store_dwordx4 v[22:23], v[26:29], off
	s_barrier
	s_cbranch_vccz .LBB0_478
.LBB0_483:
	s_waitcnt vmcnt(0)
	s_setprio 0
	s_mov_b64 s[0:1], 0
	v_writelane_b32 v255, s0, 2
	s_nop 1
	v_writelane_b32 v255, s1, 3

; #define LAS __attribute__((address_space(3)))
; #define RTID opaque_tid()
; #define ZERO_ACC8(acc, NJ_)                             \
;   _Pragma("unroll") for (int i_ = 0; i_ < 8; ++i_)      \
;   _Pragma("unroll") for (int j_ = 0; j_ < (NJ_); ++j_) { acc[i_][j_] = (f32x4){0.f, 0.f, 0.f, 0.f}; }
; template <int MI, int NJ> ...
;     ...
;   const int lrow = tid >> 3, lkc = tid & 7;
;   const u16* Ag = A + (size_t)(row0 + lrow) * lda + kbeg + lkc * 8;
;   const u16* Bg = Bt + (size_t)(col0 + lrow) * ldb + kbeg + lkc * 8;
;   const size_t a64 = (size_t)64 * lda, b64 = (size_t)64 * ldb;
;   const int nk = (kend - kbeg) >> 6;
;   const long long nAoff = (long long)(nrow0 - row0) * lda + (nkbeg - kbeg);
;   const long long nBoff = (long long)(ncol0 - col0) * ldb + (nkbeg - kbeg);
;   u16* wa = sA + lrow * 64 + ((lkc ^ (lrow & 7)) * 8);
;   u16* wb = sB + lrow * 64 + ((lkc ^ (lrow & 7)) * 8);
;     ...
;   if (!pre) G8LOADP(Ag, Bg);
; __device__ __forceinline__ void phase_ffn_up(const Params& p, const u16* Wgu, u16* smem, volatile LAS unsigned* vb_) {
;   const u16* H = (const u16*)(p.ws + OFF_H);
;   u16* act = (u16*)(p.ws + OFF_ACT);
;   const int tid = RTID;
;   const int lane = tid & 63, wave = tid >> 6;
;   const int wm = wave >> 2, wn = wave & 3;
;   const int vb = real_vb(vb_);
;   const int step = gridDim.x >> 3;
;   G8REGS_DECL;
;   bool pre = false;
;   for (int lt = vb >> 3; lt < 8 * 20; lt += step) {
;     const int nt = lt >> 3, mt = (vb & 7) * 8 + (lt & 7);
;     const int ltn = (lt + step < 8 * 20) ? lt + step : lt;
;     f32x4 acc[8][4];
;     ZERO_ACC8(acc, 4);
;     gemm8<8, 4>(acc, G8REGS_ARGS, pre, H, 1024, Wgu, 1024, 0, 1024, mt * 256, nt * 256,
;                 ((vb & 7) * 8 + (ltn & 7)) * 256, (ltn >> 3) * 256, 0, smem, tid);
.LBB0_595:
	s_nop 0
	v_readlane_b32 s0, v255, 0
	v_readlane_b32 s1, v255, 1
	s_and_b64 vcc, exec, s[0:1]
	s_cbranch_vccz .LBB0_608
	s_waitcnt vmcnt(15)
	v_mov_b32_e32 v2, v175
	ds_read_b32 v0, v230
	s_cmp_eq_u32 s82, 0
	s_cselect_b32 s0, 0, 0x1080000
	s_add_u32 s0, s72, s0
	s_addc_u32 s1, s73, 0
	s_waitcnt lgkmcnt(0)
	v_readfirstlane_b32 s37, v0
	s_ashr_i32 s36, s37, 3
	v_ashrrev_i32_e32 v176, 3, v2
	v_lshlrev_b32_e32 v3, 4, v2
	v_lshrrev_b32_e32 v4, 4, v2
	v_and_b32_e32 v5, 7, v2
	v_lshrrev_b32_e32 v180, 1, v2
	v_and_b32_e32 v179, 15, v2
	s_waitcnt vmcnt(13)
	v_lshrrev_b32_e32 v6, 2, v2
	s_mov_b32 s10, 0x1ffff80
	v_ashrrev_i32_e32 v177, 8, v2
	v_bfe_u32 v178, v2, 6, 2
	s_cmpk_gt_i32 s36, 0x9f
	v_and_b32_e32 v0, 0x70, v3
	v_xor_b32_e32 v184, v176, v2
	v_bitop3_b32 v182, v4, v5, 3 bitop3:0x6c
	v_and_or_b32 v183, v180, s10, v179
	v_and_b32_e32 v181, 12, v6
	s_cbranch_scc1 .LBB0_603
	v_lshlrev_b32_e32 v4, 4, v184
	s_lshl_b32 s10, s37, 3
	v_and_b32_e32 v4, 0x70, v4
	s_and_b32 s38, s10, 56
	v_readlane_b32 s10, v252, 38
	v_lshl_or_b32 v185, v176, 7, v4
	v_lshlrev_b32_e32 v4, 3, v182
	v_readlane_b32 s11, v252, 39
	v_xor_b32_e32 v5, 32, v4
	v_lshlrev_b32_e32 v6, 7, v2
	v_lshl_add_u64 v[162:163], s[10:11], 0, v[0:1]
	v_sub_u32_e32 v5, v5, v4
	v_lshlrev_b32_e32 v4, 4, v182
	v_and_b32_e32 v6, 0x6780, v6
	s_mov_b32 s10, 0x10000
	v_lshl_or_b32 v187, v183, 7, v4
	v_or3_b32 v188, v6, v4, s10
	v_lshlrev_b32_e32 v4, 1, v179
	v_lshl_or_b32 v8, v177, 7, v181
	v_lshl_or_b32 v4, v178, 6, v4
	v_and_b32_e32 v6, 0xf0, v3
	v_mov_b32_e32 v7, v1
	s_movk_i32 s12, 0x110
	v_lshl_add_u64 v[166:167], s[78:79], 0, v[6:7]
	v_ashrrev_i32_e32 v189, 4, v2
	v_mad_u64_u32 v[168:169], s[10:11], v8, s12, v[4:5]
	v_add_u32_e32 v4, 0x200, v2
	v_add_u32_e32 v7, 0x400, v2
	v_add_u32_e32 v8, 0x600, v2
	v_add_u32_e32 v9, 0x800, v2
	s_waitcnt vmcnt(12)
	v_add_u32_e32 v10, 0xa00, v2
	v_add_u32_e32 v11, 0xc00, v2
	v_add_u32_e32 v2, 0xe00, v2
	v_ashrrev_i32_e32 v169, 4, v4
	v_ashrrev_i32_e32 v190, 4, v7
	v_ashrrev_i32_e32 v191, 4, v8
	v_ashrrev_i32_e32 v192, 4, v9
	v_ashrrev_i32_e32 v193, 4, v10
	v_ashrrev_i32_e32 v194, 4, v11
	v_ashrrev_i32_e32 v195, 4, v2
	v_mul_lo_u32 v3, v189, s12
	v_mul_lo_u32 v4, v169, s12
	v_mul_lo_u32 v7, v190, s12
	v_mul_lo_u32 v8, v191, s12
	v_mul_lo_u32 v9, v192, s12
	v_mul_lo_u32 v10, v193, s12
	v_mul_lo_u32 v11, v194, s12
	v_mul_lo_u32 v2, v195, s12
	v_lshl_add_u64 v[164:165], s[0:1], 0, v[0:1]
	v_add_u32_e32 v186, 0x10000, v185
	s_mov_b64 s[12:13], 0
	v_lshlrev_b32_e32 v196, 1, v5
	v_add_u32_e32 v197, v6, v3
	v_add_u32_e32 v198, v6, v4
	v_add_u32_e32 v199, v6, v7
	v_add_u32_e32 v200, v6, v8
	v_add_u32_e32 v204, v6, v9
	v_add_u32_e32 v205, v6, v10
	v_add_u32_e32 v206, v6, v11
	v_add_u32_e32 v207, v6, v2
	s_mov_b32 s20, s36
	v_bfe_u32 v169, v175, 3, 3
	v_and_b32_e32 v194, 7, v175
	v_lshlrev_b32_e32 v194, 4, v194
	v_lshl_add_u32 v169, v169, 11, v194
	v_add_u32_e32 v194, 0x20000, v169
	v_add_u32_e32 v195, 0x40000, v169
	v_add_u32_e32 v198, 0x60000, v169
	v_cmp_lt_u32_e32 vcc, 0xff, v175
	s_cbranch_vccz .Lprio_skip_ffn
	s_setprio 1
.Lprio_skip_ffn:
.LBB0_598:
	s_and_b32 s22, s20, 7
	s_or_b32 s10, s22, s38
	s_lshl_b32 s39, s10, 8
	s_waitcnt vmcnt(4)
	v_add_u32_e32 v34, s39, v176
	s_ashr_i32 s40, s20, 3
	v_ashrrev_i32_e32 v35, 31, v34
	s_lshl_b32 s21, s40, 8
	v_lshlrev_b64 v[34:35], 11, v[34:35]
	v_lshl_add_u64 v[170:171], v[162:163], 0, v[34:35]
	v_add_u32_e32 v34, s21, v176
	v_ashrrev_i32_e32 v35, 31, v34
	v_lshlrev_b64 v[34:35], 11, v[34:35]
	v_lshl_add_u64 v[172:173], v[164:165], 0, v[34:35]
	v_readfirstlane_b32 s62, v170
	v_readfirstlane_b32 s63, v171
	v_readfirstlane_b32 s64, v172
	v_readfirstlane_b32 s65, v173
	s_nop 3
	s_and_b64 vcc, exec, s[12:13]
	s_cbranch_vccnz .LBB0_600
	global_load_dwordx4 v[2:5], v169, s[62:63]
	global_load_dwordx4 v[6:9], v194, s[62:63]
	global_load_dwordx4 v[10:13], v195, s[62:63]
	global_load_dwordx4 v[18:21], v198, s[62:63]
	global_load_dwordx4 v[14:17], v169, s[64:65]
	global_load_dwordx4 v[22:25], v194, s[64:65]
	global_load_dwordx4 v[26:29], v195, s[64:65]
	global_load_dwordx4 v[30:33], v198, s[64:65]

; template <int MI, int NJ> ...
;     ...
;   for (int kt = 0; kt < nk; ++kt) {
;     const int buf = kt & 1;
;     {
;       G8STORE(buf ^ 1);
;       const u16* ga_ = (kt + 2 < nk) ? Ag + (kt + 2) * 64 : Ag + nAoff;
;       const u16* gb_ = (kt + 2 < nk) ? Bg + (kt + 2) * 64 : Bg + nBoff;
;       G8LOADP(ga_, gb_);
;     }
;     __builtin_amdgcn_sched_barrier(0);
;     __builtin_amdgcn_s_setprio(1);
;     const u16* a = ra_ + buf * AROWS * 64;
;     const u16* b = rb_ + buf * BROWS * 64;
; #pragma unroll
;     for (int ks = 0; ks < 2; ++ks) {
;       const u16* a_ = ks ? a + dsw : a;
;       const u16* b_ = ks ? b + dsw : b;
;       bf16x8 bfr[NJ];
; #pragma unroll
;       for (int j = 0; j < NJ; ++j) bfr[j] = *(const bf16x8*)(b_ + j * 16 * 64);
; #pragma unroll
;       for (int ih = 0; ih < MI / 4; ++ih) {
;         bf16x8 af[4];
; #pragma unroll
;         for (int i = 0; i < 4; ++i) af[i] = *(const bf16x8*)(a_ + (ih * 4 + i) * 16 * 64);
; #pragma unroll
;         for (int i = 0; i < 4; ++i)
; #pragma unroll
;           for (int j = 0; j < NJ; ++j) acc[ih * 4 + i][j] = mfma16(af[i], bfr[j], acc[ih * 4 + i][j]);
;       }
;     }
;     __builtin_amdgcn_s_setprio(0);
;     __builtin_amdgcn_sched_barrier(0);
;     __syncthreads();
;   }
.LBB0_601:
	s_waitcnt lgkmcnt(6)
	v_mfma_f32_16x16x32_bf16 v[158:161], v[212:215], v[208:211], v[158:161]
	s_waitcnt lgkmcnt(5)
	v_mfma_f32_16x16x32_bf16 v[154:157], v[216:219], v[208:211], v[154:157]
	s_waitcnt lgkmcnt(4)
	v_mfma_f32_16x16x32_bf16 v[150:153], v[220:223], v[208:211], v[150:153]
	s_waitcnt lgkmcnt(3)
	v_mfma_f32_16x16x32_bf16 v[146:149], v[224:227], v[208:211], v[146:149]
	ds_read_b128 v[208:211], v228 offset:8192
	s_waitcnt lgkmcnt(3)
	v_mfma_f32_16x16x32_bf16 v[142:145], v[212:215], v[234:237], v[142:145]
	v_mfma_f32_16x16x32_bf16 v[138:141], v[216:219], v[234:237], v[138:141]
	v_mfma_f32_16x16x32_bf16 v[134:137], v[220:223], v[234:237], v[134:137]
	v_mfma_f32_16x16x32_bf16 v[130:133], v[224:227], v[234:237], v[130:133]
	ds_read_b128 v[234:237], v228 offset:10240
	s_waitcnt lgkmcnt(3)
	v_mfma_f32_16x16x32_bf16 v[126:129], v[212:215], v[238:241], v[126:129]
	v_mfma_f32_16x16x32_bf16 v[122:125], v[216:219], v[238:241], v[122:125]
	v_mfma_f32_16x16x32_bf16 v[118:121], v[220:223], v[238:241], v[118:121]
	v_mfma_f32_16x16x32_bf16 v[114:117], v[224:227], v[238:241], v[114:117]
	ds_read_b128 v[238:241], v228 offset:12288
	ds_read_b128 v[242:245], v229
	ds_read_b128 v[246:249], v229 offset:2048
	s_waitcnt lgkmcnt(5)
	v_mfma_f32_16x16x32_bf16 v[110:113], v[212:215], v[204:207], v[110:113]
	v_mfma_f32_16x16x32_bf16 v[106:109], v[216:219], v[204:207], v[106:109]
	v_mfma_f32_16x16x32_bf16 v[102:105], v[220:223], v[204:207], v[102:105]
	v_mfma_f32_16x16x32_bf16 v[98:101], v[224:227], v[204:207], v[98:101]
	ds_read_b128 v[204:207], v228 offset:14336
	ds_read_b128 v[190:193], v229 offset:4096
	ds_read_b128 v[170:173], v229 offset:6144
	s_waitcnt lgkmcnt(7)
	v_mfma_f32_16x16x32_bf16 v[94:97], v[212:215], v[208:211], v[94:97]
	v_mfma_f32_16x16x32_bf16 v[90:93], v[216:219], v[208:211], v[90:93]
	v_mfma_f32_16x16x32_bf16 v[86:89], v[220:223], v[208:211], v[86:89]
	v_mfma_f32_16x16x32_bf16 v[82:85], v[224:227], v[208:211], v[82:85]
	v_add_u32_e32 v228, v228, v196
	ds_read_b128 v[208:211], v228
	s_waitcnt vmcnt(7)
	ds_write_b128 v199, v[2:5]
	global_load_dwordx4 v[2:5], v169, s[50:51]
	s_waitcnt lgkmcnt(8)
	v_mfma_f32_16x16x32_bf16 v[78:81], v[212:215], v[234:237], v[78:81]
	v_mfma_f32_16x16x32_bf16 v[74:77], v[216:219], v[234:237], v[74:77]
	v_mfma_f32_16x16x32_bf16 v[70:73], v[220:223], v[234:237], v[70:73]
	v_mfma_f32_16x16x32_bf16 v[66:69], v[224:227], v[234:237], v[66:69]
	ds_read_b128 v[234:237], v228 offset:2048
	s_waitcnt vmcnt(7)
	ds_write_b128 v199, v[6:9] offset:8192
	global_load_dwordx4 v[6:9], v194, s[50:51]
	s_waitcnt lgkmcnt(9)
	v_mfma_f32_16x16x32_bf16 v[62:65], v[212:215], v[238:241], v[62:65]
	v_mfma_f32_16x16x32_bf16 v[58:61], v[216:219], v[238:241], v[58:61]
	v_mfma_f32_16x16x32_bf16 v[54:57], v[220:223], v[238:241], v[54:57]
	v_mfma_f32_16x16x32_bf16 v[50:53], v[224:227], v[238:241], v[50:53]
	ds_read_b128 v[238:241], v228 offset:4096
	s_waitcnt vmcnt(7)
	ds_write_b128 v199, v[10:13] offset:16384
	global_load_dwordx4 v[10:13], v195, s[50:51]
	s_waitcnt lgkmcnt(8)
	v_mfma_f32_16x16x32_bf16 v[46:49], v[212:215], v[204:207], v[46:49]
	v_mfma_f32_16x16x32_bf16 v[42:45], v[216:219], v[204:207], v[42:45]
	v_mfma_f32_16x16x32_bf16 v[38:41], v[220:223], v[204:207], v[38:41]
	v_mfma_f32_16x16x32_bf16 v[34:37], v[224:227], v[204:207], v[34:37]
	ds_read_b128 v[204:207], v228 offset:6144
	s_waitcnt vmcnt(7)
	ds_write_b128 v199, v[18:21] offset:24576
	global_load_dwordx4 v[18:21], v198, s[50:51]
	s_waitcnt lgkmcnt(7)
	v_mfma_f32_16x16x32_bf16 v[158:161], v[242:245], v[208:211], v[158:161]
	v_mfma_f32_16x16x32_bf16 v[154:157], v[246:249], v[208:211], v[154:157]
	v_mfma_f32_16x16x32_bf16 v[150:153], v[190:193], v[208:211], v[150:153]
	v_mfma_f32_16x16x32_bf16 v[146:149], v[170:173], v[208:211], v[146:149]
	ds_read_b128 v[208:211], v228 offset:8192
	s_waitcnt vmcnt(7)
	ds_write_b128 v200, v[14:17]
	global_load_dwordx4 v[14:17], v169, s[52:53]
	s_waitcnt lgkmcnt(7)
	v_mfma_f32_16x16x32_bf16 v[142:145], v[242:245], v[234:237], v[142:145]
	v_mfma_f32_16x16x32_bf16 v[138:141], v[246:249], v[234:237], v[138:141]
	v_mfma_f32_16x16x32_bf16 v[134:137], v[190:193], v[234:237], v[134:137]
	v_mfma_f32_16x16x32_bf16 v[130:133], v[170:173], v[234:237], v[130:133]
	ds_read_b128 v[234:237], v228 offset:10240
	s_waitcnt vmcnt(7)
	ds_write_b128 v200, v[22:25] offset:8192
	global_load_dwordx4 v[22:25], v194, s[52:53]
	s_waitcnt lgkmcnt(7)
	v_mfma_f32_16x16x32_bf16 v[126:129], v[242:245], v[238:241], v[126:129]
	v_mfma_f32_16x16x32_bf16 v[122:125], v[246:249], v[238:241], v[122:125]
	v_mfma_f32_16x16x32_bf16 v[118:121], v[190:193], v[238:241], v[118:121]
	v_mfma_f32_16x16x32_bf16 v[114:117], v[170:173], v[238:241], v[114:117]
	ds_read_b128 v[238:241], v228 offset:12288
	s_waitcnt vmcnt(7)
	ds_write_b128 v200, v[26:29] offset:16384
	global_load_dwordx4 v[26:29], v195, s[52:53]
	s_waitcnt lgkmcnt(7)
	v_mfma_f32_16x16x32_bf16 v[110:113], v[242:245], v[204:207], v[110:113]
	v_mfma_f32_16x16x32_bf16 v[106:109], v[246:249], v[204:207], v[106:109]
	v_mfma_f32_16x16x32_bf16 v[102:105], v[190:193], v[204:207], v[102:105]
	v_mfma_f32_16x16x32_bf16 v[98:101], v[170:173], v[204:207], v[98:101]
	ds_read_b128 v[204:207], v228 offset:14336
	s_waitcnt vmcnt(7)
	ds_write_b128 v200, v[30:33] offset:24576
	global_load_dwordx4 v[30:33], v198, s[52:53]
	s_waitcnt lgkmcnt(7)
	v_mfma_f32_16x16x32_bf16 v[94:97], v[242:245], v[208:211], v[94:97]
	v_mfma_f32_16x16x32_bf16 v[90:93], v[246:249], v[208:211], v[90:93]
	v_mfma_f32_16x16x32_bf16 v[86:89], v[190:193], v[208:211], v[86:89]
	v_mfma_f32_16x16x32_bf16 v[82:85], v[170:173], v[208:211], v[82:85]
	s_waitcnt lgkmcnt(0)
	s_barrier
; __device__ __forceinline__ float siluf_(float x) { return x / (1.0f + __expf(-x)); }
; template <int MI, int NJ> ...
;     ...
;     const u16* a = ra_ + buf * AROWS * 64;
;     const u16* b = rb_ + buf * BROWS * 64;
; #pragma unroll
;     for (int ks = 0; ks < 2; ++ks) {
;       const u16* a_ = ks ? a + dsw : a;
;       const u16* b_ = ks ? b + dsw : b;
;       bf16x8 bfr[NJ];
; #pragma unroll
;       for (int j = 0; j < NJ; ++j) bfr[j] = *(const bf16x8*)(b_ + j * 16 * 64);
; #pragma unroll
;       for (int ih = 0; ih < MI / 4; ++ih) {
;         bf16x8 af[4];
; #pragma unroll
;         for (int i = 0; i < 4; ++i) af[i] = *(const bf16x8*)(a_ + (ih * 4 + i) * 16 * 64);
; #pragma unroll
;         for (int i = 0; i < 4; ++i)
; #pragma unroll
;           for (int j = 0; j < NJ; ++j) acc[ih * 4 + i][j] = mfma16(af[i], bfr[j], acc[ih * 4 + i][j]);
;       }
;     }
; __device__ __forceinline__ void phase_ffn_up(const Params& p, const u16* Wgu, u16* smem, volatile LAS unsigned* vb_) {
;     ...
; #pragma unroll
;     for (int i = 0; i < 8; ++i)
; #pragma unroll
;       for (int jp = 0; jp < 2; ++jp) {
; #pragma unroll
;         for (int r = 0; r < 4; ++r) {
;           const float g = acc[i][2 * jp][r], u = acc[i][2 * jp + 1][r];
;           smem[(wm * 128 + i * 16 + (lane >> 4) * 4 + r) * 136 + (wn * 2 + jp) * 16 + (lane & 15)] = f2bf(siluf_(g) * u);
;         }
;         __builtin_amdgcn_sched_barrier(0);
;       }
	s_add_i32 s43, s43, 1
	s_add_u32 s22, s22, 64
	s_addc_u32 s23, s23, 0
	s_addk_i32 s42, 0x4000
	s_and_b32 s48, s42, 0x4000
	s_xor_b32 s44, s48, 0x4000
	s_lshl_b32 s44, s44, 1
	v_add_u32_e32 v199, s44, v185
	v_add_u32_e32 v200, s44, v186
	s_cmp_lt_u32 s43, 14
	s_cselect_b32 s45, s23, s13
	s_cselect_b32 s44, s22, s12
	s_cselect_b32 s47, s23, s21
	s_cselect_b32 s46, s22, s20
	s_lshl_b64 s[44:45], s[44:45], 1
	s_lshl_b64 s[46:47], s[46:47], 1
	s_add_u32 s50, s62, s44
	s_addc_u32 s51, s63, s45
	s_add_u32 s52, s64, s46
	s_addc_u32 s53, s65, s47
	s_lshl_b32 s44, s48, 1
	v_add_u32_e32 v228, s44, v187
	v_add_u32_e32 v229, s44, v188
	ds_read_b128 v[212:215], v229
	ds_read_b128 v[208:211], v228
	ds_read_b128 v[216:219], v229 offset:2048
	ds_read_b128 v[220:223], v229 offset:4096
	ds_read_b128 v[224:227], v229 offset:6144
	v_mfma_f32_16x16x32_bf16 v[78:81], v[242:245], v[234:237], v[78:81]
	v_mfma_f32_16x16x32_bf16 v[74:77], v[246:249], v[234:237], v[74:77]
	v_mfma_f32_16x16x32_bf16 v[70:73], v[190:193], v[234:237], v[70:73]
	v_mfma_f32_16x16x32_bf16 v[66:69], v[170:173], v[234:237], v[66:69]
	ds_read_b128 v[234:237], v228 offset:2048
	v_mfma_f32_16x16x32_bf16 v[62:65], v[242:245], v[238:241], v[62:65]
	v_mfma_f32_16x16x32_bf16 v[58:61], v[246:249], v[238:241], v[58:61]
	v_mfma_f32_16x16x32_bf16 v[54:57], v[190:193], v[238:241], v[54:57]
	v_mfma_f32_16x16x32_bf16 v[50:53], v[170:173], v[238:241], v[50:53]
	ds_read_b128 v[238:241], v228 offset:4096
	v_mfma_f32_16x16x32_bf16 v[46:49], v[242:245], v[204:207], v[46:49]
	v_mfma_f32_16x16x32_bf16 v[42:45], v[246:249], v[204:207], v[42:45]
	v_mfma_f32_16x16x32_bf16 v[38:41], v[190:193], v[204:207], v[38:41]
	v_mfma_f32_16x16x32_bf16 v[34:37], v[170:173], v[204:207], v[34:37]
	ds_read_b128 v[204:207], v228 offset:6144
	v_add_u32_e32 v229, v229, v196
	s_cmpk_lg_i32 s22, 0x480
	s_cbranch_scc1 .LBB0_601
	v_and_b32_e32 v228, 15, v175
	v_bfe_u32 v229, v175, 8, 1
	v_lshl_or_b32 v228, v229, 7, v228
	v_mul_u32_u24_e32 v228, 0x110, v228
	v_bfe_u32 v229, v175, 6, 2
	v_lshl_add_u32 v228, v229, 6, v228
	v_bfe_u32 v229, v175, 4, 2
	v_lshl_add_u32 v228, v229, 3, v228
	v_mul_f32_e32 v208, 0xbfb8aa3b, v158
	v_mul_f32_e32 v209, 0xbfb8aa3b, v159
	v_mul_f32_e32 v210, 0xbfb8aa3b, v160
	v_mul_f32_e32 v211, 0xbfb8aa3b, v161
	v_mul_f32_e32 v212, 0xbfb8aa3b, v150
	v_mul_f32_e32 v213, 0xbfb8aa3b, v151
	v_mul_f32_e32 v214, 0xbfb8aa3b, v152
	v_mul_f32_e32 v215, 0xbfb8aa3b, v153
	v_min_f32_e32 v208, 0x42fc0000, v208
	v_min_f32_e32 v209, 0x42fc0000, v209
	v_min_f32_e32 v210, 0x42fc0000, v210
	v_min_f32_e32 v211, 0x42fc0000, v211
	v_min_f32_e32 v212, 0x42fc0000, v212
	v_min_f32_e32 v213, 0x42fc0000, v213
	v_min_f32_e32 v214, 0x42fc0000, v214
	v_min_f32_e32 v215, 0x42fc0000, v215
	v_exp_f32_e32 v208, v208
	v_exp_f32_e32 v209, v209
	v_exp_f32_e32 v210, v210
	v_exp_f32_e32 v211, v211
	v_exp_f32_e32 v212, v212
	v_exp_f32_e32 v213, v213
	v_exp_f32_e32 v214, v214
	v_exp_f32_e32 v215, v215
	v_add_f32_e32 v208, 1.0, v208
	v_add_f32_e32 v209, 1.0, v209
	v_add_f32_e32 v210, 1.0, v210
	v_add_f32_e32 v211, 1.0, v211
	v_add_f32_e32 v212, 1.0, v212
	v_add_f32_e32 v213, 1.0, v213
	v_add_f32_e32 v214, 1.0, v214
	v_add_f32_e32 v215, 1.0, v215
	v_rcp_f32_e32 v216, v208
	v_rcp_f32_e32 v217, v209
	v_rcp_f32_e32 v218, v210
	v_rcp_f32_e32 v219, v211
	v_rcp_f32_e32 v220, v212
	v_rcp_f32_e32 v221, v213
	v_rcp_f32_e32 v222, v214
	v_rcp_f32_e32 v223, v215
	v_fma_f32 v208, -v208, v216, 1.0
	v_fma_f32 v209, -v209, v217, 1.0
	v_fma_f32 v210, -v210, v218, 1.0
	v_fma_f32 v211, -v211, v219, 1.0
	v_fma_f32 v212, -v212, v220, 1.0
	v_fma_f32 v213, -v213, v221, 1.0
	v_fma_f32 v214, -v214, v222, 1.0
	v_fma_f32 v215, -v215, v223, 1.0
	v_fmac_f32_e32 v216, v208, v216
	v_fmac_f32_e32 v217, v209, v217
	v_fmac_f32_e32 v218, v210, v218
	v_fmac_f32_e32 v219, v211, v219
	v_fmac_f32_e32 v220, v212, v220
	v_fmac_f32_e32 v221, v213, v221
	v_fmac_f32_e32 v222, v214, v222
	v_fmac_f32_e32 v223, v215, v223
	v_mul_f32_e32 v158, v158, v216
	v_mul_f32_e32 v159, v159, v217
	v_mul_f32_e32 v160, v160, v218
	v_mul_f32_e32 v161, v161, v219
	v_mul_f32_e32 v150, v150, v220
	v_mul_f32_e32 v151, v151, v221
	v_mul_f32_e32 v152, v152, v222
	v_mul_f32_e32 v153, v153, v223
	v_mul_f32_e32 v158, v158, v154
	v_mul_f32_e32 v159, v159, v155
	v_mul_f32_e32 v160, v160, v156
	v_mul_f32_e32 v161, v161, v157
	v_mul_f32_e32 v150, v150, v146
	v_mul_f32_e32 v151, v151, v147
	v_mul_f32_e32 v152, v152, v148
	v_mul_f32_e32 v153, v153, v149
	v_cvt_pk_bf16_f32 v158, v158, v159
	v_cvt_pk_bf16_f32 v159, v160, v161
	v_cvt_pk_bf16_f32 v150, v150, v151
	v_cvt_pk_bf16_f32 v151, v152, v153
	ds_write_b64 v228, v[158:159]
	ds_write_b64 v228, v[150:151] offset:32
	v_mul_f32_e32 v208, 0xbfb8aa3b, v142
	v_mul_f32_e32 v209, 0xbfb8aa3b, v143
	v_mul_f32_e32 v210, 0xbfb8aa3b, v144
	v_mul_f32_e32 v211, 0xbfb8aa3b, v145
	v_mul_f32_e32 v212, 0xbfb8aa3b, v134
	v_mul_f32_e32 v213, 0xbfb8aa3b, v135
	v_mul_f32_e32 v214, 0xbfb8aa3b, v136
	v_mul_f32_e32 v215, 0xbfb8aa3b, v137
	v_min_f32_e32 v208, 0x42fc0000, v208
	v_min_f32_e32 v209, 0x42fc0000, v209
	v_min_f32_e32 v210, 0x42fc0000, v210
	v_min_f32_e32 v211, 0x42fc0000, v211
	v_min_f32_e32 v212, 0x42fc0000, v212
	v_min_f32_e32 v213, 0x42fc0000, v213
	v_min_f32_e32 v214, 0x42fc0000, v214
	v_min_f32_e32 v215, 0x42fc0000, v215
	v_exp_f32_e32 v208, v208
	v_exp_f32_e32 v209, v209
	v_exp_f32_e32 v210, v210
	v_exp_f32_e32 v211, v211
	v_exp_f32_e32 v212, v212
	v_exp_f32_e32 v213, v213
	v_exp_f32_e32 v214, v214
	v_exp_f32_e32 v215, v215
	v_add_f32_e32 v208, 1.0, v208
	v_add_f32_e32 v209, 1.0, v209
	v_add_f32_e32 v210, 1.0, v210
	v_add_f32_e32 v211, 1.0, v211
	v_add_f32_e32 v212, 1.0, v212
; __device__ __forceinline__ float siluf_(float x) { return x / (1.0f + __expf(-x)); }
; __device__ __forceinline__ void phase_ffn_up(const Params& p, const u16* Wgu, u16* smem, volatile LAS unsigned* vb_) {
;     ...
; #pragma unroll
;     for (int i = 0; i < 8; ++i)
; #pragma unroll
;       for (int jp = 0; jp < 2; ++jp) {
; #pragma unroll
;         for (int r = 0; r < 4; ++r) {
;           const float g = acc[i][2 * jp][r], u = acc[i][2 * jp + 1][r];
;           smem[(wm * 128 + i * 16 + (lane >> 4) * 4 + r) * 136 + (wn * 2 + jp) * 16 + (lane & 15)] = f2bf(siluf_(g) * u);
;         }
;         __builtin_amdgcn_sched_barrier(0);
;       }
	v_add_f32_e32 v213, 1.0, v213
	v_add_f32_e32 v214, 1.0, v214
	v_add_f32_e32 v215, 1.0, v215
	v_rcp_f32_e32 v216, v208
	v_rcp_f32_e32 v217, v209
	v_rcp_f32_e32 v218, v210
	v_rcp_f32_e32 v219, v211
	v_rcp_f32_e32 v220, v212
	v_rcp_f32_e32 v221, v213
	v_rcp_f32_e32 v222, v214
	v_rcp_f32_e32 v223, v215
	v_fma_f32 v208, -v208, v216, 1.0
	v_fma_f32 v209, -v209, v217, 1.0
	v_fma_f32 v210, -v210, v218, 1.0
	v_fma_f32 v211, -v211, v219, 1.0
	v_fma_f32 v212, -v212, v220, 1.0
	v_fma_f32 v213, -v213, v221, 1.0
	v_fma_f32 v214, -v214, v222, 1.0
	v_fma_f32 v215, -v215, v223, 1.0
	v_fmac_f32_e32 v216, v208, v216
	v_fmac_f32_e32 v217, v209, v217
	v_fmac_f32_e32 v218, v210, v218
	v_fmac_f32_e32 v219, v211, v219
	v_fmac_f32_e32 v220, v212, v220
	v_fmac_f32_e32 v221, v213, v221
	v_fmac_f32_e32 v222, v214, v222
	v_fmac_f32_e32 v223, v215, v223
	v_mul_f32_e32 v142, v142, v216
	v_mul_f32_e32 v143, v143, v217
	v_mul_f32_e32 v144, v144, v218
	v_mul_f32_e32 v145, v145, v219
	v_mul_f32_e32 v134, v134, v220
	v_mul_f32_e32 v135, v135, v221
	v_mul_f32_e32 v136, v136, v222
	v_mul_f32_e32 v137, v137, v223
	v_mul_f32_e32 v142, v142, v138
	v_mul_f32_e32 v143, v143, v139
	v_mul_f32_e32 v144, v144, v140
	v_mul_f32_e32 v145, v145, v141
	v_mul_f32_e32 v134, v134, v130
	v_mul_f32_e32 v135, v135, v131
	v_mul_f32_e32 v136, v136, v132
	v_mul_f32_e32 v137, v137, v133
	v_cvt_pk_bf16_f32 v142, v142, v143
	v_cvt_pk_bf16_f32 v143, v144, v145
	v_cvt_pk_bf16_f32 v134, v134, v135
	v_cvt_pk_bf16_f32 v135, v136, v137
	ds_write_b64 v228, v[142:143] offset:4352
	ds_write_b64 v228, v[134:135] offset:4384
	v_mul_f32_e32 v208, 0xbfb8aa3b, v126
	v_mul_f32_e32 v209, 0xbfb8aa3b, v127
	v_mul_f32_e32 v210, 0xbfb8aa3b, v128
	v_mul_f32_e32 v211, 0xbfb8aa3b, v129
	v_mul_f32_e32 v212, 0xbfb8aa3b, v118
	v_mul_f32_e32 v213, 0xbfb8aa3b, v119
	v_mul_f32_e32 v214, 0xbfb8aa3b, v120
	v_mul_f32_e32 v215, 0xbfb8aa3b, v121
	v_min_f32_e32 v208, 0x42fc0000, v208
	v_min_f32_e32 v209, 0x42fc0000, v209
	v_min_f32_e32 v210, 0x42fc0000, v210
	v_min_f32_e32 v211, 0x42fc0000, v211
	v_min_f32_e32 v212, 0x42fc0000, v212
	v_min_f32_e32 v213, 0x42fc0000, v213
	v_min_f32_e32 v214, 0x42fc0000, v214
	v_min_f32_e32 v215, 0x42fc0000, v215
	v_exp_f32_e32 v208, v208
	v_exp_f32_e32 v209, v209
	v_exp_f32_e32 v210, v210
	v_exp_f32_e32 v211, v211
	v_exp_f32_e32 v212, v212
	v_exp_f32_e32 v213, v213
	v_exp_f32_e32 v214, v214
	v_exp_f32_e32 v215, v215
	v_add_f32_e32 v208, 1.0, v208
	v_add_f32_e32 v209, 1.0, v209
	v_add_f32_e32 v210, 1.0, v210
	v_add_f32_e32 v211, 1.0, v211
	v_add_f32_e32 v212, 1.0, v212
	v_add_f32_e32 v213, 1.0, v213
	v_add_f32_e32 v214, 1.0, v214
	v_add_f32_e32 v215, 1.0, v215
	v_rcp_f32_e32 v216, v208
	v_rcp_f32_e32 v217, v209
	v_rcp_f32_e32 v218, v210
	v_rcp_f32_e32 v219, v211
	v_rcp_f32_e32 v220, v212
	v_rcp_f32_e32 v221, v213
	v_rcp_f32_e32 v222, v214
	v_rcp_f32_e32 v223, v215
	v_fma_f32 v208, -v208, v216, 1.0
	v_fma_f32 v209, -v209, v217, 1.0
	v_fma_f32 v210, -v210, v218, 1.0
	v_fma_f32 v211, -v211, v219, 1.0
	v_fma_f32 v212, -v212, v220, 1.0
	v_fma_f32 v213, -v213, v221, 1.0
	v_fma_f32 v214, -v214, v222, 1.0
	v_fma_f32 v215, -v215, v223, 1.0
	v_fmac_f32_e32 v216, v208, v216
	v_fmac_f32_e32 v217, v209, v217
	v_fmac_f32_e32 v218, v210, v218
	v_fmac_f32_e32 v219, v211, v219
	v_fmac_f32_e32 v220, v212, v220
	v_fmac_f32_e32 v221, v213, v221
	v_fmac_f32_e32 v222, v214, v222
	v_fmac_f32_e32 v223, v215, v223
	v_mul_f32_e32 v126, v126, v216
	v_mul_f32_e32 v127, v127, v217
	v_mul_f32_e32 v128, v128, v218
	v_mul_f32_e32 v129, v129, v219
	v_mul_f32_e32 v118, v118, v220
	v_mul_f32_e32 v119, v119, v221
	v_mul_f32_e32 v120, v120, v222
	v_mul_f32_e32 v121, v121, v223
	v_mul_f32_e32 v126, v126, v122
	v_mul_f32_e32 v127, v127, v123
	v_mul_f32_e32 v128, v128, v124
	v_mul_f32_e32 v129, v129, v125
	v_mul_f32_e32 v118, v118, v114
	v_mul_f32_e32 v119, v119, v115
	v_mul_f32_e32 v120, v120, v116
	v_mul_f32_e32 v121, v121, v117
	v_cvt_pk_bf16_f32 v126, v126, v127
	v_cvt_pk_bf16_f32 v127, v128, v129
	v_cvt_pk_bf16_f32 v118, v118, v119
	v_cvt_pk_bf16_f32 v119, v120, v121
	ds_write_b64 v228, v[126:127] offset:8704
	ds_write_b64 v228, v[118:119] offset:8736
	v_mul_f32_e32 v208, 0xbfb8aa3b, v110
	v_mul_f32_e32 v209, 0xbfb8aa3b, v111
	v_mul_f32_e32 v210, 0xbfb8aa3b, v112
	v_mul_f32_e32 v211, 0xbfb8aa3b, v113
	v_mul_f32_e32 v212, 0xbfb8aa3b, v102
	v_mul_f32_e32 v213, 0xbfb8aa3b, v103
	v_mul_f32_e32 v214, 0xbfb8aa3b, v104
	v_mul_f32_e32 v215, 0xbfb8aa3b, v105
	v_min_f32_e32 v208, 0x42fc0000, v208
	v_min_f32_e32 v209, 0x42fc0000, v209
	v_min_f32_e32 v210, 0x42fc0000, v210
	v_min_f32_e32 v211, 0x42fc0000, v211
	v_min_f32_e32 v212, 0x42fc0000, v212
	v_min_f32_e32 v213, 0x42fc0000, v213
	v_min_f32_e32 v214, 0x42fc0000, v214
	v_min_f32_e32 v215, 0x42fc0000, v215
	v_exp_f32_e32 v208, v208
	v_exp_f32_e32 v209, v209
	v_exp_f32_e32 v210, v210
	v_exp_f32_e32 v211, v211
	v_exp_f32_e32 v212, v212
	v_exp_f32_e32 v213, v213
	v_exp_f32_e32 v214, v214
	v_exp_f32_e32 v215, v215
	v_add_f32_e32 v208, 1.0, v208
	v_add_f32_e32 v209, 1.0, v209
	v_add_f32_e32 v210, 1.0, v210
	v_add_f32_e32 v211, 1.0, v211
	v_add_f32_e32 v212, 1.0, v212
	v_add_f32_e32 v213, 1.0, v213
	v_add_f32_e32 v214, 1.0, v214
	v_add_f32_e32 v215, 1.0, v215
	v_rcp_f32_e32 v216, v208
	v_rcp_f32_e32 v217, v209
	v_rcp_f32_e32 v218, v210
	v_rcp_f32_e32 v219, v211
	v_rcp_f32_e32 v220, v212
	v_rcp_f32_e32 v221, v213
	v_rcp_f32_e32 v222, v214
	v_rcp_f32_e32 v223, v215
	v_fma_f32 v208, -v208, v216, 1.0
	v_fma_f32 v209, -v209, v217, 1.0
	v_fma_f32 v210, -v210, v218, 1.0
	v_fma_f32 v211, -v211, v219, 1.0
	v_fma_f32 v212, -v212, v220, 1.0
	v_fma_f32 v213, -v213, v221, 1.0
	v_fma_f32 v214, -v214, v222, 1.0
; __device__ __forceinline__ float siluf_(float x) { return x / (1.0f + __expf(-x)); }
; __device__ __forceinline__ void phase_ffn_up(const Params& p, const u16* Wgu, u16* smem, volatile LAS unsigned* vb_) {
;     ...
; #pragma unroll
;     for (int i = 0; i < 8; ++i)
; #pragma unroll
;       for (int jp = 0; jp < 2; ++jp) {
; #pragma unroll
;         for (int r = 0; r < 4; ++r) {
;           const float g = acc[i][2 * jp][r], u = acc[i][2 * jp + 1][r];
;           smem[(wm * 128 + i * 16 + (lane >> 4) * 4 + r) * 136 + (wn * 2 + jp) * 16 + (lane & 15)] = f2bf(siluf_(g) * u);
;         }
;         __builtin_amdgcn_sched_barrier(0);
;       }
	v_fma_f32 v215, -v215, v223, 1.0
	v_fmac_f32_e32 v216, v208, v216
	v_fmac_f32_e32 v217, v209, v217
	v_fmac_f32_e32 v218, v210, v218
	v_fmac_f32_e32 v219, v211, v219
	v_fmac_f32_e32 v220, v212, v220
	v_fmac_f32_e32 v221, v213, v221
	v_fmac_f32_e32 v222, v214, v222
	v_fmac_f32_e32 v223, v215, v223
	v_mul_f32_e32 v110, v110, v216
	v_mul_f32_e32 v111, v111, v217
	v_mul_f32_e32 v112, v112, v218
	v_mul_f32_e32 v113, v113, v219
	v_mul_f32_e32 v102, v102, v220
	v_mul_f32_e32 v103, v103, v221
	v_mul_f32_e32 v104, v104, v222
	v_mul_f32_e32 v105, v105, v223
	v_mul_f32_e32 v110, v110, v106
	v_mul_f32_e32 v111, v111, v107
	v_mul_f32_e32 v112, v112, v108
	v_mul_f32_e32 v113, v113, v109
	v_mul_f32_e32 v102, v102, v98
	v_mul_f32_e32 v103, v103, v99
	v_mul_f32_e32 v104, v104, v100
	v_mul_f32_e32 v105, v105, v101
	v_cvt_pk_bf16_f32 v110, v110, v111
	v_cvt_pk_bf16_f32 v111, v112, v113
	v_cvt_pk_bf16_f32 v102, v102, v103
	v_cvt_pk_bf16_f32 v103, v104, v105
	ds_write_b64 v228, v[110:111] offset:13056
	ds_write_b64 v228, v[102:103] offset:13088
	v_mul_f32_e32 v208, 0xbfb8aa3b, v94
	v_mul_f32_e32 v209, 0xbfb8aa3b, v95
	v_mul_f32_e32 v210, 0xbfb8aa3b, v96
	v_mul_f32_e32 v211, 0xbfb8aa3b, v97
	v_mul_f32_e32 v212, 0xbfb8aa3b, v86
	v_mul_f32_e32 v213, 0xbfb8aa3b, v87
	v_mul_f32_e32 v214, 0xbfb8aa3b, v88
	v_mul_f32_e32 v215, 0xbfb8aa3b, v89
	v_min_f32_e32 v208, 0x42fc0000, v208
	v_min_f32_e32 v209, 0x42fc0000, v209
	v_min_f32_e32 v210, 0x42fc0000, v210
	v_min_f32_e32 v211, 0x42fc0000, v211
	v_min_f32_e32 v212, 0x42fc0000, v212
	v_min_f32_e32 v213, 0x42fc0000, v213
	v_min_f32_e32 v214, 0x42fc0000, v214
	v_min_f32_e32 v215, 0x42fc0000, v215
	v_exp_f32_e32 v208, v208
	v_exp_f32_e32 v209, v209
	v_exp_f32_e32 v210, v210
	v_exp_f32_e32 v211, v211
	v_exp_f32_e32 v212, v212
	v_exp_f32_e32 v213, v213
	v_exp_f32_e32 v214, v214
	v_exp_f32_e32 v215, v215
	v_add_f32_e32 v208, 1.0, v208
	v_add_f32_e32 v209, 1.0, v209
	v_add_f32_e32 v210, 1.0, v210
	v_add_f32_e32 v211, 1.0, v211
	v_add_f32_e32 v212, 1.0, v212
	v_add_f32_e32 v213, 1.0, v213
	v_add_f32_e32 v214, 1.0, v214
	v_add_f32_e32 v215, 1.0, v215
	v_rcp_f32_e32 v216, v208
	v_rcp_f32_e32 v217, v209
	v_rcp_f32_e32 v218, v210
	v_rcp_f32_e32 v219, v211
	v_rcp_f32_e32 v220, v212
	v_rcp_f32_e32 v221, v213
	v_rcp_f32_e32 v222, v214
	v_rcp_f32_e32 v223, v215
	v_fma_f32 v208, -v208, v216, 1.0
	v_fma_f32 v209, -v209, v217, 1.0
	v_fma_f32 v210, -v210, v218, 1.0
	v_fma_f32 v211, -v211, v219, 1.0
	v_fma_f32 v212, -v212, v220, 1.0
	v_fma_f32 v213, -v213, v221, 1.0
	v_fma_f32 v214, -v214, v222, 1.0
	v_fma_f32 v215, -v215, v223, 1.0
	v_fmac_f32_e32 v216, v208, v216
	v_fmac_f32_e32 v217, v209, v217
	v_fmac_f32_e32 v218, v210, v218
	v_fmac_f32_e32 v219, v211, v219
	v_fmac_f32_e32 v220, v212, v220
	v_fmac_f32_e32 v221, v213, v221
	v_fmac_f32_e32 v222, v214, v222
	v_fmac_f32_e32 v223, v215, v223
	v_mul_f32_e32 v94, v94, v216
	v_mul_f32_e32 v95, v95, v217
	v_mul_f32_e32 v96, v96, v218
	v_mul_f32_e32 v97, v97, v219
	v_mul_f32_e32 v86, v86, v220
	v_mul_f32_e32 v87, v87, v221
	v_mul_f32_e32 v88, v88, v222
	v_mul_f32_e32 v89, v89, v223
	v_mul_f32_e32 v94, v94, v90
	v_mul_f32_e32 v95, v95, v91
	v_mul_f32_e32 v96, v96, v92
	v_mul_f32_e32 v97, v97, v93
	v_mul_f32_e32 v86, v86, v82
	v_mul_f32_e32 v87, v87, v83
	v_mul_f32_e32 v88, v88, v84
	v_mul_f32_e32 v89, v89, v85
	v_cvt_pk_bf16_f32 v94, v94, v95
	v_cvt_pk_bf16_f32 v95, v96, v97
	v_cvt_pk_bf16_f32 v86, v86, v87
	v_cvt_pk_bf16_f32 v87, v88, v89
	ds_write_b64 v228, v[94:95] offset:17408
	ds_write_b64 v228, v[86:87] offset:17440
	v_mul_f32_e32 v208, 0xbfb8aa3b, v78
	v_mul_f32_e32 v209, 0xbfb8aa3b, v79
	v_mul_f32_e32 v210, 0xbfb8aa3b, v80
	v_mul_f32_e32 v211, 0xbfb8aa3b, v81
	v_mul_f32_e32 v212, 0xbfb8aa3b, v70
	v_mul_f32_e32 v213, 0xbfb8aa3b, v71
	v_mul_f32_e32 v214, 0xbfb8aa3b, v72
	v_mul_f32_e32 v215, 0xbfb8aa3b, v73
	v_min_f32_e32 v208, 0x42fc0000, v208
	v_min_f32_e32 v209, 0x42fc0000, v209
	v_min_f32_e32 v210, 0x42fc0000, v210
	v_min_f32_e32 v211, 0x42fc0000, v211
	v_min_f32_e32 v212, 0x42fc0000, v212
	v_min_f32_e32 v213, 0x42fc0000, v213
	v_min_f32_e32 v214, 0x42fc0000, v214
	v_min_f32_e32 v215, 0x42fc0000, v215
	v_exp_f32_e32 v208, v208
	v_exp_f32_e32 v209, v209
	v_exp_f32_e32 v210, v210
	v_exp_f32_e32 v211, v211
	v_exp_f32_e32 v212, v212
	v_exp_f32_e32 v213, v213
	v_exp_f32_e32 v214, v214
	v_exp_f32_e32 v215, v215
	v_add_f32_e32 v208, 1.0, v208
	v_add_f32_e32 v209, 1.0, v209
	v_add_f32_e32 v210, 1.0, v210
	v_add_f32_e32 v211, 1.0, v211
	v_add_f32_e32 v212, 1.0, v212
	v_add_f32_e32 v213, 1.0, v213
	v_add_f32_e32 v214, 1.0, v214
	v_add_f32_e32 v215, 1.0, v215
	v_rcp_f32_e32 v216, v208
	v_rcp_f32_e32 v217, v209
	v_rcp_f32_e32 v218, v210
	v_rcp_f32_e32 v219, v211
	v_rcp_f32_e32 v220, v212
	v_rcp_f32_e32 v221, v213
	v_rcp_f32_e32 v222, v214
	v_rcp_f32_e32 v223, v215
	v_fma_f32 v208, -v208, v216, 1.0
	v_fma_f32 v209, -v209, v217, 1.0
	v_fma_f32 v210, -v210, v218, 1.0
	v_fma_f32 v211, -v211, v219, 1.0
	v_fma_f32 v212, -v212, v220, 1.0
	v_fma_f32 v213, -v213, v221, 1.0
	v_fma_f32 v214, -v214, v222, 1.0
	v_fma_f32 v215, -v215, v223, 1.0
	v_fmac_f32_e32 v216, v208, v216
	v_fmac_f32_e32 v217, v209, v217
	v_fmac_f32_e32 v218, v210, v218
	v_fmac_f32_e32 v219, v211, v219
	v_fmac_f32_e32 v220, v212, v220
	v_fmac_f32_e32 v221, v213, v221
	v_fmac_f32_e32 v222, v214, v222
	v_fmac_f32_e32 v223, v215, v223
	v_mul_f32_e32 v78, v78, v216
	v_mul_f32_e32 v79, v79, v217
	v_mul_f32_e32 v80, v80, v218
	v_mul_f32_e32 v81, v81, v219
	v_mul_f32_e32 v70, v70, v220
	v_mul_f32_e32 v71, v71, v221
	v_mul_f32_e32 v72, v72, v222
	v_mul_f32_e32 v73, v73, v223
	v_mul_f32_e32 v78, v78, v74
	v_mul_f32_e32 v79, v79, v75
; __device__ __forceinline__ float siluf_(float x) { return x / (1.0f + __expf(-x)); }
; __device__ __forceinline__ void phase_ffn_up(const Params& p, const u16* Wgu, u16* smem, volatile LAS unsigned* vb_) {
;     ...
; #pragma unroll
;     for (int i = 0; i < 8; ++i)
; #pragma unroll
;       for (int jp = 0; jp < 2; ++jp) {
; #pragma unroll
;         for (int r = 0; r < 4; ++r) {
;           const float g = acc[i][2 * jp][r], u = acc[i][2 * jp + 1][r];
;           smem[(wm * 128 + i * 16 + (lane >> 4) * 4 + r) * 136 + (wn * 2 + jp) * 16 + (lane & 15)] = f2bf(siluf_(g) * u);
;         }
;         __builtin_amdgcn_sched_barrier(0);
;       }
;     __syncthreads();
	v_mul_f32_e32 v80, v80, v76
	v_mul_f32_e32 v81, v81, v77
	v_mul_f32_e32 v70, v70, v66
	v_mul_f32_e32 v71, v71, v67
	v_mul_f32_e32 v72, v72, v68
	v_mul_f32_e32 v73, v73, v69
	v_cvt_pk_bf16_f32 v78, v78, v79
	v_cvt_pk_bf16_f32 v79, v80, v81
	v_cvt_pk_bf16_f32 v70, v70, v71
	v_cvt_pk_bf16_f32 v71, v72, v73
	ds_write_b64 v228, v[78:79] offset:21760
	ds_write_b64 v228, v[70:71] offset:21792
	v_mul_f32_e32 v208, 0xbfb8aa3b, v62
	v_mul_f32_e32 v209, 0xbfb8aa3b, v63
	v_mul_f32_e32 v210, 0xbfb8aa3b, v64
	v_mul_f32_e32 v211, 0xbfb8aa3b, v65
	v_mul_f32_e32 v212, 0xbfb8aa3b, v54
	v_mul_f32_e32 v213, 0xbfb8aa3b, v55
	v_mul_f32_e32 v214, 0xbfb8aa3b, v56
	v_mul_f32_e32 v215, 0xbfb8aa3b, v57
	v_min_f32_e32 v208, 0x42fc0000, v208
	v_min_f32_e32 v209, 0x42fc0000, v209
	v_min_f32_e32 v210, 0x42fc0000, v210
	v_min_f32_e32 v211, 0x42fc0000, v211
	v_min_f32_e32 v212, 0x42fc0000, v212
	v_min_f32_e32 v213, 0x42fc0000, v213
	v_min_f32_e32 v214, 0x42fc0000, v214
	v_min_f32_e32 v215, 0x42fc0000, v215
	v_exp_f32_e32 v208, v208
	v_exp_f32_e32 v209, v209
	v_exp_f32_e32 v210, v210
	v_exp_f32_e32 v211, v211
	v_exp_f32_e32 v212, v212
	v_exp_f32_e32 v213, v213
	v_exp_f32_e32 v214, v214
	v_exp_f32_e32 v215, v215
	v_add_f32_e32 v208, 1.0, v208
	v_add_f32_e32 v209, 1.0, v209
	v_add_f32_e32 v210, 1.0, v210
	v_add_f32_e32 v211, 1.0, v211
	v_add_f32_e32 v212, 1.0, v212
	v_add_f32_e32 v213, 1.0, v213
	v_add_f32_e32 v214, 1.0, v214
	v_add_f32_e32 v215, 1.0, v215
	v_rcp_f32_e32 v216, v208
	v_rcp_f32_e32 v217, v209
	v_rcp_f32_e32 v218, v210
	v_rcp_f32_e32 v219, v211
	v_rcp_f32_e32 v220, v212
	v_rcp_f32_e32 v221, v213
	v_rcp_f32_e32 v222, v214
	v_rcp_f32_e32 v223, v215
	v_fma_f32 v208, -v208, v216, 1.0
	v_fma_f32 v209, -v209, v217, 1.0
	v_fma_f32 v210, -v210, v218, 1.0
	v_fma_f32 v211, -v211, v219, 1.0
	v_fma_f32 v212, -v212, v220, 1.0
	v_fma_f32 v213, -v213, v221, 1.0
	v_fma_f32 v214, -v214, v222, 1.0
	v_fma_f32 v215, -v215, v223, 1.0
	v_fmac_f32_e32 v216, v208, v216
	v_fmac_f32_e32 v217, v209, v217
	v_fmac_f32_e32 v218, v210, v218
	v_fmac_f32_e32 v219, v211, v219
	v_fmac_f32_e32 v220, v212, v220
	v_fmac_f32_e32 v221, v213, v221
	v_fmac_f32_e32 v222, v214, v222
	v_fmac_f32_e32 v223, v215, v223
	v_mul_f32_e32 v62, v62, v216
	v_mul_f32_e32 v63, v63, v217
	v_mul_f32_e32 v64, v64, v218
	v_mul_f32_e32 v65, v65, v219
	v_mul_f32_e32 v54, v54, v220
	v_mul_f32_e32 v55, v55, v221
	v_mul_f32_e32 v56, v56, v222
	v_mul_f32_e32 v57, v57, v223
	v_mul_f32_e32 v62, v62, v58
	v_mul_f32_e32 v63, v63, v59
	v_mul_f32_e32 v64, v64, v60
	v_mul_f32_e32 v65, v65, v61
	v_mul_f32_e32 v54, v54, v50
	v_mul_f32_e32 v55, v55, v51
	v_mul_f32_e32 v56, v56, v52
	v_mul_f32_e32 v57, v57, v53
	v_cvt_pk_bf16_f32 v62, v62, v63
	v_cvt_pk_bf16_f32 v63, v64, v65
	v_cvt_pk_bf16_f32 v54, v54, v55
	v_cvt_pk_bf16_f32 v55, v56, v57
	ds_write_b64 v228, v[62:63] offset:26112
	ds_write_b64 v228, v[54:55] offset:26144
	v_mul_f32_e32 v208, 0xbfb8aa3b, v46
	v_mul_f32_e32 v209, 0xbfb8aa3b, v47
	v_mul_f32_e32 v210, 0xbfb8aa3b, v48
	v_mul_f32_e32 v211, 0xbfb8aa3b, v49
	v_mul_f32_e32 v212, 0xbfb8aa3b, v38
	v_mul_f32_e32 v213, 0xbfb8aa3b, v39
	v_mul_f32_e32 v214, 0xbfb8aa3b, v40
	v_mul_f32_e32 v215, 0xbfb8aa3b, v41
	v_min_f32_e32 v208, 0x42fc0000, v208
	v_min_f32_e32 v209, 0x42fc0000, v209
	v_min_f32_e32 v210, 0x42fc0000, v210
	v_min_f32_e32 v211, 0x42fc0000, v211
	v_min_f32_e32 v212, 0x42fc0000, v212
	v_min_f32_e32 v213, 0x42fc0000, v213
	v_min_f32_e32 v214, 0x42fc0000, v214
	v_min_f32_e32 v215, 0x42fc0000, v215
	v_exp_f32_e32 v208, v208
	v_exp_f32_e32 v209, v209
	v_exp_f32_e32 v210, v210
	v_exp_f32_e32 v211, v211
	v_exp_f32_e32 v212, v212
	v_exp_f32_e32 v213, v213
	v_exp_f32_e32 v214, v214
	v_exp_f32_e32 v215, v215
	v_add_f32_e32 v208, 1.0, v208
	v_add_f32_e32 v209, 1.0, v209
	v_add_f32_e32 v210, 1.0, v210
	v_add_f32_e32 v211, 1.0, v211
	v_add_f32_e32 v212, 1.0, v212
	v_add_f32_e32 v213, 1.0, v213
	v_add_f32_e32 v214, 1.0, v214
	v_add_f32_e32 v215, 1.0, v215
	v_rcp_f32_e32 v216, v208
	v_rcp_f32_e32 v217, v209
	v_rcp_f32_e32 v218, v210
	v_rcp_f32_e32 v219, v211
	v_rcp_f32_e32 v220, v212
	v_rcp_f32_e32 v221, v213
	v_rcp_f32_e32 v222, v214
	v_rcp_f32_e32 v223, v215
	v_fma_f32 v208, -v208, v216, 1.0
	v_fma_f32 v209, -v209, v217, 1.0
	v_fma_f32 v210, -v210, v218, 1.0
	v_fma_f32 v211, -v211, v219, 1.0
	v_fma_f32 v212, -v212, v220, 1.0
	v_fma_f32 v213, -v213, v221, 1.0
	v_fma_f32 v214, -v214, v222, 1.0
	v_fma_f32 v215, -v215, v223, 1.0
	v_fmac_f32_e32 v216, v208, v216
	v_fmac_f32_e32 v217, v209, v217
	v_fmac_f32_e32 v218, v210, v218
	v_fmac_f32_e32 v219, v211, v219
	v_fmac_f32_e32 v220, v212, v220
	v_fmac_f32_e32 v221, v213, v221
	v_fmac_f32_e32 v222, v214, v222
	v_fmac_f32_e32 v223, v215, v223
	v_mul_f32_e32 v46, v46, v216
	v_mul_f32_e32 v47, v47, v217
	v_mul_f32_e32 v48, v48, v218
	v_mul_f32_e32 v49, v49, v219
	v_mul_f32_e32 v38, v38, v220
	v_mul_f32_e32 v39, v39, v221
	v_mul_f32_e32 v40, v40, v222
	v_mul_f32_e32 v41, v41, v223
	v_mul_f32_e32 v46, v46, v42
	v_mul_f32_e32 v47, v47, v43
	v_mul_f32_e32 v48, v48, v44
	v_mul_f32_e32 v49, v49, v45
	v_mul_f32_e32 v38, v38, v34
	v_mul_f32_e32 v39, v39, v35
	v_mul_f32_e32 v40, v40, v36
	v_mul_f32_e32 v41, v41, v37
	v_cvt_pk_bf16_f32 v46, v46, v47
	v_cvt_pk_bf16_f32 v47, v48, v49
	v_cvt_pk_bf16_f32 v38, v38, v39
	v_cvt_pk_bf16_f32 v39, v40, v41
	ds_write_b64 v228, v[46:47] offset:30464
	ds_write_b64 v228, v[38:39] offset:30496
	s_waitcnt lgkmcnt(0)
	s_barrier
; #define ZERO_ACC8(acc, NJ_)                             \
;   _Pragma("unroll") for (int i_ = 0; i_ < 8; ++i_)      \
;   _Pragma("unroll") for (int j_ = 0; j_ < (NJ_); ++j_) { acc[i_][j_] = (f32x4){0.f, 0.f, 0.f, 0.f}; }
; __device__ __forceinline__ void phase_ffn_up(const Params& p, const u16* Wgu, u16* smem, volatile LAS unsigned* vb_) {
;     ...
; #pragma unroll
;     for (int k = 0; k < 8; ++k) {
;       const int c = tid + 512 * k;
;       const int row = c >> 4, ch = c & 15;
;       const uint4 v = *(const uint4*)(smem + row * 136 + ch * 8);
;       *(uint4*)(act + (size_t)(mt * 256 + row) * DFF + nt * 128 + ch * 8) = v;
;     }
;     __syncthreads();
;     ...
;   for (int lt = vb >> 3; lt < 8 * 4; lt += step) {
;     const int hn = lt >> 3, mt = (vb & 7) * 8 + (lt & 7);
;     f32x4 acc[8][2];
;     ZERO_ACC8(acc, 2);
;     G8REGS_DECL;
;     R_b2 = R_b3 = make_uint4(0u, 0u, 0u, 0u);
;     gemm8<8, 2>(acc, G8REGS_ARGS, false, H, 1024, Wgu, 1024, 0, 1024, mt * 256, 5120 + hn * 128, mt * 256, 5120 + hn * 128, 0, smem, tid);
	s_lshl_b32 s12, s40, 7
	s_ashr_i32 s13, s12, 31
	v_lshl_add_u64 v[38:39], s[12:13], 1, v[166:167]
	s_and_b64 vcc, exec, s[10:11]
	s_mov_b32 s20, s41
	ds_read_b128 v[34:37], v197
	s_add_i32 s49, s39, 0
	v_add_u32_e32 v40, s49, v189
	v_mad_i64_i32 v[40:41], s[12:13], v40, s7, v[38:39]
	s_waitcnt lgkmcnt(0)
	global_store_dwordx4 v[40:41], v[34:37], off
	ds_read_b128 v[34:37], v197 offset:8704
	s_add_i32 s49, s39, 32
	v_add_u32_e32 v40, s49, v189
	v_mad_i64_i32 v[40:41], s[12:13], v40, s7, v[38:39]
	s_waitcnt lgkmcnt(0)
	global_store_dwordx4 v[40:41], v[34:37], off
	ds_read_b128 v[34:37], v197 offset:17408
	s_add_i32 s49, s39, 64
	v_add_u32_e32 v40, s49, v189
	v_mad_i64_i32 v[40:41], s[12:13], v40, s7, v[38:39]
	s_waitcnt lgkmcnt(0)
	global_store_dwordx4 v[40:41], v[34:37], off
	ds_read_b128 v[34:37], v197 offset:26112
	s_add_i32 s49, s39, 96
	v_add_u32_e32 v40, s49, v189
	v_mad_i64_i32 v[40:41], s[12:13], v40, s7, v[38:39]
	s_waitcnt lgkmcnt(0)
	global_store_dwordx4 v[40:41], v[34:37], off
	ds_read_b128 v[34:37], v197 offset:34816
	s_add_i32 s49, s39, 128
	v_add_u32_e32 v40, s49, v189
	v_mad_i64_i32 v[40:41], s[12:13], v40, s7, v[38:39]
	s_waitcnt lgkmcnt(0)
	global_store_dwordx4 v[40:41], v[34:37], off
	ds_read_b128 v[34:37], v197 offset:43520
	s_add_i32 s49, s39, 160
	v_add_u32_e32 v40, s49, v189
	v_mad_i64_i32 v[40:41], s[12:13], v40, s7, v[38:39]
	s_waitcnt lgkmcnt(0)
	global_store_dwordx4 v[40:41], v[34:37], off
	ds_read_b128 v[34:37], v197 offset:52224
	s_add_i32 s49, s39, 192
	v_add_u32_e32 v40, s49, v189
	v_mad_i64_i32 v[40:41], s[12:13], v40, s7, v[38:39]
	s_waitcnt lgkmcnt(0)
	global_store_dwordx4 v[40:41], v[34:37], off
	ds_read_b128 v[34:37], v197 offset:60928
	s_add_i32 s49, s39, 224
	v_add_u32_e32 v40, s49, v189
	v_mad_i64_i32 v[40:41], s[12:13], v40, s7, v[38:39]
	s_waitcnt lgkmcnt(0)
	global_store_dwordx4 v[40:41], v[34:37], off
	s_mov_b64 s[12:13], -1
	s_barrier
	s_cbranch_vccz .LBB0_598
.LBB0_603:
	s_waitcnt vmcnt(0)
	s_setprio 0
	s_cmp_gt_i32 s36, 31
	s_cbranch_scc1 .LBB0_608
	v_readlane_b32 s12, v252, 38
	v_readlane_b32 s13, v252, 39
	s_waitcnt vmcnt(15)
	v_lshlrev_b32_e32 v2, 3, v182
	v_lshl_add_u64 v[92:93], s[0:1], 0, v[0:1]
	v_lshl_add_u64 v[90:91], s[12:13], 0, v[0:1]
	v_lshlrev_b32_e32 v0, 4, v184
	v_xor_b32_e32 v3, 32, v2
	v_and_or_b32 v4, v180, s9, v179
	v_and_b32_e32 v0, 0x70, v0
	v_sub_u32_e32 v2, v3, v2
	v_lshlrev_b32_e32 v3, 4, v182
	v_lshlrev_b32_e32 v4, 7, v4
	s_mov_b32 s0, 0x10000
	s_lshl_b32 s10, s37, 3
	v_lshl_or_b32 v0, v176, 7, v0
	v_lshl_or_b32 v100, v183, 7, v3
	v_or3_b32 v101, v4, v3, s0
	v_lshlrev_b32_e32 v3, 4, v178
	s_movk_i32 s0, 0xa00
	s_and_b32 s10, s10, 56
	v_add_u32_e32 v98, 0x1400, v176
	v_add_u32_e32 v99, 0x10000, v0
	v_lshl_or_b32 v102, v177, 7, v181
	v_or3_b32 v103, v3, v179, s0
	v_lshlrev_b32_e32 v104, 1, v2
